# v83 + LDS m0 bases folded to ldsw+const (6 fewer SALU per K-loop iteration)
# baseline (speedup 1.0000x reference)
.LBB0_173:
	ds_read_b128 v[144:147], v155
	ds_read_b128 v[148:151], v155 offset:1024
	ds_read_b128 v[158:161], v155 offset:2048
	ds_read_b128 v[162:165], v155 offset:3072
	ds_read_b128 v[166:169], v156
	ds_read_b128 v[170:173], v156 offset:1024
	ds_read_b128 v[174:177], v156 offset:2048
	ds_read_b128 v[178:181], v156 offset:3072
	s_add_u32 s68, s66, 0xfff80080
	s_addc_u32 s69, s67, -1
	s_cmp_eq_u32 s77, 28
	s_cselect_b32 s71, s55, s69
	s_cselect_b32 s70, s59, s68
	s_cselect_b32 s69, s57, s76
	s_cselect_b32 s68, s65, s73
	s_add_i32 m0, s25, 0xc000
	ds_read_b128 v[182:185], v157
	ds_read_b128 v[186:189], v157 offset:1024
	ds_read_b128 v[190:193], v157 offset:2048
	ds_read_b128 v[194:197], v157 offset:3072
	ds_read_b128 v[198:201], v157 offset:4096
	ds_read_b128 v[202:205], v157 offset:5120
	ds_read_b128 v[206:209], v157 offset:6144
	global_load_lds_dwordx4 v136, s[66:67]
	s_add_i32 m0, s25, 0xe000
	ds_read_b128 v[210:213], v157 offset:7168
	global_load_lds_dwordx4 v138, s[66:67]
	s_waitcnt vmcnt(8) lgkmcnt(0)
	s_setprio 1
	s_barrier
	v_mfma_i32_16x16x64_i8 v[124:127], v[144:147], v[182:185], v[124:127]
	v_mfma_i32_16x16x64_i8 v[116:119], v[158:161], v[182:185], v[116:119]
	v_mfma_i32_16x16x64_i8 v[108:111], v[144:147], v[190:193], v[108:111]
	v_mfma_i32_16x16x64_i8 v[100:103], v[158:161], v[190:193], v[100:103]
	v_mfma_i32_16x16x64_i8 v[92:95], v[144:147], v[198:201], v[92:95]
	v_mfma_i32_16x16x64_i8 v[84:87], v[158:161], v[198:201], v[84:87]
	v_mfma_i32_16x16x64_i8 v[76:79], v[144:147], v[206:209], v[76:79]
	v_mfma_i32_16x16x64_i8 v[68:71], v[158:161], v[206:209], v[68:71]
	v_mfma_i32_16x16x64_i8 v[124:127], v[148:151], v[186:189], v[124:127]
	v_mfma_i32_16x16x64_i8 v[116:119], v[162:165], v[186:189], v[116:119]
	v_mfma_i32_16x16x64_i8 v[108:111], v[148:151], v[194:197], v[108:111]
	v_mfma_i32_16x16x64_i8 v[100:103], v[162:165], v[194:197], v[100:103]
	v_mfma_i32_16x16x64_i8 v[92:95], v[148:151], v[202:205], v[92:95]
	v_mfma_i32_16x16x64_i8 v[84:87], v[162:165], v[202:205], v[84:87]
	v_mfma_i32_16x16x64_i8 v[76:79], v[148:151], v[210:213], v[76:79]
	v_mfma_i32_16x16x64_i8 v[68:71], v[162:165], v[210:213], v[68:71]
	v_mfma_i32_16x16x64_i8 v[120:123], v[166:169], v[182:185], v[120:123]
	v_mfma_i32_16x16x64_i8 v[112:115], v[174:177], v[182:185], v[112:115]
	v_mfma_i32_16x16x64_i8 v[104:107], v[166:169], v[190:193], v[104:107]
	v_mfma_i32_16x16x64_i8 v[96:99], v[174:177], v[190:193], v[96:99]
	v_mfma_i32_16x16x64_i8 v[88:91], v[166:169], v[198:201], v[88:91]
	v_mfma_i32_16x16x64_i8 v[80:83], v[174:177], v[198:201], v[80:83]
	v_mfma_i32_16x16x64_i8 v[72:75], v[166:169], v[206:209], v[72:75]
	v_mfma_i32_16x16x64_i8 v[64:67], v[174:177], v[206:209], v[64:67]
	v_mfma_i32_16x16x64_i8 v[120:123], v[170:173], v[186:189], v[120:123]
	v_mfma_i32_16x16x64_i8 v[112:115], v[178:181], v[186:189], v[112:115]
	v_mfma_i32_16x16x64_i8 v[104:107], v[170:173], v[194:197], v[104:107]
	v_mfma_i32_16x16x64_i8 v[96:99], v[178:181], v[194:197], v[96:99]
	v_mfma_i32_16x16x64_i8 v[88:91], v[170:173], v[202:205], v[88:91]
	v_mfma_i32_16x16x64_i8 v[80:83], v[178:181], v[202:205], v[80:83]
	v_mfma_i32_16x16x64_i8 v[72:75], v[170:173], v[210:213], v[72:75]
	v_mfma_i32_16x16x64_i8 v[64:67], v[178:181], v[210:213], v[64:67]
	s_barrier
	s_setprio 0
	s_add_i32 m0, s25, 0x10000
	ds_read_b128 v[182:185], v157 offset:16384
	ds_read_b128 v[186:189], v157 offset:17408
	ds_read_b128 v[190:193], v157 offset:18432
	ds_read_b128 v[194:197], v157 offset:19456
	ds_read_b128 v[198:201], v157 offset:20480
	global_load_lds_dwordx4 v132, s[68:69]
	s_add_i32 m0, s25, 0x12000
	s_add_u32 s78, s68, 0x80000
	s_mov_b64 s[98:99], s[68:69]
	s_addc_u32 s79, s69, 0
	global_load_lds_dwordx4 v128, s[98:99]
	s_add_i32 m0, s25, 0x14000
	s_mov_b64 s[100:101], s[70:71]
	global_load_lds_dwordx4 v132, s[78:79]
	s_add_i32 m0, s25, 0x16000
	ds_read_b128 v[202:205], v157 offset:21504
	global_load_lds_dwordx4 v128, s[78:79]
	s_mov_b64 s[100:101], s[70:71]
	s_mov_b32 m0, s25
	ds_read_b128 v[206:209], v157 offset:22528
	global_load_lds_dwordx4 v134, s[100:101]
	s_mov_b32 m0, s26
	ds_read_b128 v[210:213], v157 offset:23552
	global_load_lds_dwordx4 v130, s[100:101]
	s_waitcnt vmcnt(8) lgkmcnt(0)
	s_setprio 1
	s_barrier
	v_mfma_i32_16x16x64_i8 v[60:63], v[144:147], v[182:185], v[60:63]
	v_mfma_i32_16x16x64_i8 v[52:55], v[158:161], v[182:185], v[52:55]
	v_mfma_i32_16x16x64_i8 v[44:47], v[144:147], v[190:193], v[44:47]
	v_mfma_i32_16x16x64_i8 v[36:39], v[158:161], v[190:193], v[36:39]
	v_mfma_i32_16x16x64_i8 v[28:31], v[144:147], v[198:201], v[28:31]
	v_mfma_i32_16x16x64_i8 v[20:23], v[158:161], v[198:201], v[20:23]
	v_mfma_i32_16x16x64_i8 v[12:15], v[144:147], v[206:209], v[12:15]
	v_mfma_i32_16x16x64_i8 v[4:7], v[158:161], v[206:209], v[4:7]
	v_mfma_i32_16x16x64_i8 v[60:63], v[148:151], v[186:189], v[60:63]
	v_mfma_i32_16x16x64_i8 v[52:55], v[162:165], v[186:189], v[52:55]
	v_mfma_i32_16x16x64_i8 v[44:47], v[148:151], v[194:197], v[44:47]
	v_mfma_i32_16x16x64_i8 v[36:39], v[162:165], v[194:197], v[36:39]
	v_mfma_i32_16x16x64_i8 v[28:31], v[148:151], v[202:205], v[28:31]
	v_mfma_i32_16x16x64_i8 v[20:23], v[162:165], v[202:205], v[20:23]
	v_mfma_i32_16x16x64_i8 v[12:15], v[148:151], v[210:213], v[12:15]
	v_mfma_i32_16x16x64_i8 v[4:7], v[162:165], v[210:213], v[4:7]
	v_mfma_i32_16x16x64_i8 v[56:59], v[166:169], v[182:185], v[56:59]
	v_mfma_i32_16x16x64_i8 v[48:51], v[174:177], v[182:185], v[48:51]
	v_mfma_i32_16x16x64_i8 v[40:43], v[166:169], v[190:193], v[40:43]
	v_mfma_i32_16x16x64_i8 v[32:35], v[174:177], v[190:193], v[32:35]
	v_mfma_i32_16x16x64_i8 v[24:27], v[166:169], v[198:201], v[24:27]
	v_mfma_i32_16x16x64_i8 v[16:19], v[174:177], v[198:201], v[16:19]
	v_mfma_i32_16x16x64_i8 v[8:11], v[166:169], v[206:209], v[8:11]
	v_mfma_i32_16x16x64_i8 v[0:3], v[174:177], v[206:209], v[0:3]
	v_mfma_i32_16x16x64_i8 v[56:59], v[170:173], v[186:189], v[56:59]
	v_mfma_i32_16x16x64_i8 v[48:51], v[178:181], v[186:189], v[48:51]
	v_mfma_i32_16x16x64_i8 v[40:43], v[170:173], v[194:197], v[40:43]
	v_mfma_i32_16x16x64_i8 v[32:35], v[178:181], v[194:197], v[32:35]
	v_mfma_i32_16x16x64_i8 v[24:27], v[170:173], v[202:205], v[24:27]
	v_mfma_i32_16x16x64_i8 v[16:19], v[178:181], v[202:205], v[16:19]
	v_mfma_i32_16x16x64_i8 v[8:11], v[170:173], v[210:213], v[8:11]
	v_mfma_i32_16x16x64_i8 v[0:3], v[178:181], v[210:213], v[0:3]
	s_barrier
	s_setprio 0
	ds_read_b128 v[144:147], v155 offset:32768
	ds_read_b128 v[148:151], v155 offset:33792
	ds_read_b128 v[158:161], v155 offset:34816
	ds_read_b128 v[162:165], v155 offset:35840
	ds_read_b128 v[166:169], v156 offset:32768
	ds_read_b128 v[170:173], v156 offset:33792
	ds_read_b128 v[174:177], v156 offset:34816
	ds_read_b128 v[178:181], v156 offset:35840
	s_add_u32 s70, s70, 0x80000
	s_addc_u32 s71, s71, 0
	s_mov_b32 m0, s27
	ds_read_b128 v[182:185], v157 offset:32768
	ds_read_b128 v[186:189], v157 offset:33792
	ds_read_b128 v[190:193], v157 offset:34816
	ds_read_b128 v[194:197], v157 offset:35840
	ds_read_b128 v[198:201], v157 offset:36864
	ds_read_b128 v[202:205], v157 offset:37888
	ds_read_b128 v[206:209], v157 offset:38912
	global_load_lds_dwordx4 v134, s[70:71]
	s_mov_b32 m0, s28
	ds_read_b128 v[210:213], v157 offset:39936
	global_load_lds_dwordx4 v130, s[70:71]
	s_waitcnt vmcnt(8) lgkmcnt(0)
	s_setprio 1
	s_barrier
	v_mfma_i32_16x16x64_i8 v[124:127], v[144:147], v[182:185], v[124:127]
	v_mfma_i32_16x16x64_i8 v[116:119], v[158:161], v[182:185], v[116:119]
	v_mfma_i32_16x16x64_i8 v[108:111], v[144:147], v[190:193], v[108:111]
	v_mfma_i32_16x16x64_i8 v[100:103], v[158:161], v[190:193], v[100:103]
	v_mfma_i32_16x16x64_i8 v[92:95], v[144:147], v[198:201], v[92:95]
	v_mfma_i32_16x16x64_i8 v[84:87], v[158:161], v[198:201], v[84:87]
	v_mfma_i32_16x16x64_i8 v[76:79], v[144:147], v[206:209], v[76:79]
	v_mfma_i32_16x16x64_i8 v[68:71], v[158:161], v[206:209], v[68:71]
	v_mfma_i32_16x16x64_i8 v[124:127], v[148:151], v[186:189], v[124:127]
	v_mfma_i32_16x16x64_i8 v[116:119], v[162:165], v[186:189], v[116:119]
	v_mfma_i32_16x16x64_i8 v[108:111], v[148:151], v[194:197], v[108:111]
	v_mfma_i32_16x16x64_i8 v[100:103], v[162:165], v[194:197], v[100:103]
	v_mfma_i32_16x16x64_i8 v[92:95], v[148:151], v[202:205], v[92:95]
	v_mfma_i32_16x16x64_i8 v[84:87], v[162:165], v[202:205], v[84:87]
	v_mfma_i32_16x16x64_i8 v[76:79], v[148:151], v[210:213], v[76:79]
	v_mfma_i32_16x16x64_i8 v[68:71], v[162:165], v[210:213], v[68:71]
	v_mfma_i32_16x16x64_i8 v[120:123], v[166:169], v[182:185], v[120:123]
	v_mfma_i32_16x16x64_i8 v[112:115], v[174:177], v[182:185], v[112:115]
	v_mfma_i32_16x16x64_i8 v[104:107], v[166:169], v[190:193], v[104:107]
	v_mfma_i32_16x16x64_i8 v[96:99], v[174:177], v[190:193], v[96:99]
	v_mfma_i32_16x16x64_i8 v[88:91], v[166:169], v[198:201], v[88:91]
	v_mfma_i32_16x16x64_i8 v[80:83], v[174:177], v[198:201], v[80:83]
	v_mfma_i32_16x16x64_i8 v[72:75], v[166:169], v[206:209], v[72:75]
	v_mfma_i32_16x16x64_i8 v[64:67], v[174:177], v[206:209], v[64:67]
	v_mfma_i32_16x16x64_i8 v[120:123], v[170:173], v[186:189], v[120:123]
	v_mfma_i32_16x16x64_i8 v[112:115], v[178:181], v[186:189], v[112:115]
	v_mfma_i32_16x16x64_i8 v[104:107], v[170:173], v[194:197], v[104:107]
	v_mfma_i32_16x16x64_i8 v[96:99], v[178:181], v[194:197], v[96:99]
	v_mfma_i32_16x16x64_i8 v[88:91], v[170:173], v[202:205], v[88:91]
	v_mfma_i32_16x16x64_i8 v[80:83], v[178:181], v[202:205], v[80:83]
	v_mfma_i32_16x16x64_i8 v[72:75], v[170:173], v[210:213], v[72:75]
	v_mfma_i32_16x16x64_i8 v[64:67], v[178:181], v[210:213], v[64:67]
	s_barrier
	s_setprio 0
	s_add_i32 m0, s25, 0x17f80
	ds_read_b128 v[182:185], v157 offset:49152
	ds_read_b128 v[186:189], v157 offset:50176
	ds_read_b128 v[190:193], v157 offset:51200
	ds_read_b128 v[194:197], v157 offset:52224
	global_load_lds_dwordx4 v132, s[68:69] offset:128
	s_add_i32 m0, s25, 0x19f80
	s_add_u32 s68, s68, 0x80080
	s_addc_u32 s69, s69, 0
	global_load_lds_dwordx4 v128, s[98:99] offset:128
	s_add_i32 m0, s25, 0x1c000
	ds_read_b128 v[198:201], v157 offset:53248
	global_load_lds_dwordx4 v132, s[68:69]
	s_add_i32 m0, s25, 0x1e000
	ds_read_b128 v[202:205], v157 offset:54272
	global_load_lds_dwordx4 v128, s[68:69]
	s_add_i32 m0, s31, -128
	ds_read_b128 v[206:209], v157 offset:55296
	global_load_lds_dwordx4 v134, s[100:101] offset:128
	s_add_i32 m0, s33, -128
	ds_read_b128 v[210:213], v157 offset:56320
	global_load_lds_dwordx4 v130, s[100:101] offset:128
	s_waitcnt vmcnt(8) lgkmcnt(0)
	s_setprio 1
	s_barrier
	v_mfma_i32_16x16x64_i8 v[60:63], v[144:147], v[182:185], v[60:63]
	v_mfma_i32_16x16x64_i8 v[52:55], v[158:161], v[182:185], v[52:55]
	v_mfma_i32_16x16x64_i8 v[44:47], v[144:147], v[190:193], v[44:47]
	v_mfma_i32_16x16x64_i8 v[36:39], v[158:161], v[190:193], v[36:39]
	v_mfma_i32_16x16x64_i8 v[28:31], v[144:147], v[198:201], v[28:31]
	v_mfma_i32_16x16x64_i8 v[20:23], v[158:161], v[198:201], v[20:23]
	v_mfma_i32_16x16x64_i8 v[12:15], v[144:147], v[206:209], v[12:15]
	v_mfma_i32_16x16x64_i8 v[4:7], v[158:161], v[206:209], v[4:7]
	v_mfma_i32_16x16x64_i8 v[60:63], v[148:151], v[186:189], v[60:63]
	v_mfma_i32_16x16x64_i8 v[52:55], v[162:165], v[186:189], v[52:55]
	v_mfma_i32_16x16x64_i8 v[44:47], v[148:151], v[194:197], v[44:47]
	v_mfma_i32_16x16x64_i8 v[36:39], v[162:165], v[194:197], v[36:39]
	v_mfma_i32_16x16x64_i8 v[28:31], v[148:151], v[202:205], v[28:31]
	v_mfma_i32_16x16x64_i8 v[20:23], v[162:165], v[202:205], v[20:23]
	v_mfma_i32_16x16x64_i8 v[12:15], v[148:151], v[210:213], v[12:15]
	v_mfma_i32_16x16x64_i8 v[4:7], v[162:165], v[210:213], v[4:7]
	v_mfma_i32_16x16x64_i8 v[56:59], v[166:169], v[182:185], v[56:59]
	v_mfma_i32_16x16x64_i8 v[48:51], v[174:177], v[182:185], v[48:51]
	v_mfma_i32_16x16x64_i8 v[40:43], v[166:169], v[190:193], v[40:43]
	v_mfma_i32_16x16x64_i8 v[32:35], v[174:177], v[190:193], v[32:35]
	v_mfma_i32_16x16x64_i8 v[24:27], v[166:169], v[198:201], v[24:27]
	v_mfma_i32_16x16x64_i8 v[16:19], v[174:177], v[198:201], v[16:19]
	v_mfma_i32_16x16x64_i8 v[8:11], v[166:169], v[206:209], v[8:11]
	v_mfma_i32_16x16x64_i8 v[0:3], v[174:177], v[206:209], v[0:3]
	v_mfma_i32_16x16x64_i8 v[56:59], v[170:173], v[186:189], v[56:59]
	v_mfma_i32_16x16x64_i8 v[48:51], v[178:181], v[186:189], v[48:51]
	v_mfma_i32_16x16x64_i8 v[40:43], v[170:173], v[194:197], v[40:43]
	v_mfma_i32_16x16x64_i8 v[32:35], v[178:181], v[194:197], v[32:35]
	v_mfma_i32_16x16x64_i8 v[24:27], v[170:173], v[202:205], v[24:27]
	v_mfma_i32_16x16x64_i8 v[16:19], v[178:181], v[202:205], v[16:19]
	v_mfma_i32_16x16x64_i8 v[8:11], v[170:173], v[210:213], v[8:11]
	v_mfma_i32_16x16x64_i8 v[0:3], v[178:181], v[210:213], v[0:3]
	s_barrier
	s_setprio 0
	s_add_i32 s77, s77, 2
	s_add_u32 s66, s66, 0x100
	s_addc_u32 s67, s67, 0
	s_add_u32 s73, s73, 0x100
	s_addc_u32 s76, s76, 0
	s_cmp_gt_u32 s77, 29
	s_cbranch_scc0 .LBB0_173
	s_and_b64 vcc, exec, s[20:21]
	s_cbranch_vccz .LBB0_176
	s_barrier

.LBB0_258:
	ds_read_b128 v[152:155], v149
	ds_read_b128 v[156:159], v149 offset:1024
	ds_read_b128 v[160:163], v149 offset:2048
	ds_read_b128 v[164:167], v149 offset:3072
	ds_read_b128 v[168:171], v150
	ds_read_b128 v[172:175], v150 offset:1024
	ds_read_b128 v[176:179], v150 offset:2048
	ds_read_b128 v[180:183], v150 offset:3072
	s_add_u32 s36, s22, 0x100
	s_addc_u32 s37, s23, 0
	s_cmpk_eq_i32 s62, 0xa8
	s_cselect_b32 s57, s5, s37
	s_cselect_b32 s56, s4, s36
	s_cselect_b32 s41, s21, s61
	s_cselect_b32 s40, s20, s60
	s_add_i32 m0, s25, 0xc000
	ds_read_b128 v[184:187], v151
	ds_read_b128 v[188:191], v151 offset:1024
	ds_read_b128 v[192:195], v151 offset:2048
	ds_read_b128 v[196:199], v151 offset:3072
	ds_read_b128 v[200:203], v151 offset:4096
	ds_read_b128 v[204:207], v151 offset:5120
	ds_read_b128 v[208:211], v151 offset:6144
	global_load_lds_dwordx4 v136, s[22:23]
	s_add_i32 m0, s25, 0xe000
	ds_read_b128 v[212:215], v151 offset:7168
	global_load_lds_dwordx4 v138, s[22:23]
	s_waitcnt vmcnt(8) lgkmcnt(0)
	s_setprio 1
	s_barrier
	v_mfma_f32_16x16x32_bf16 v[124:127], v[152:155], v[184:187], v[124:127]
	v_mfma_f32_16x16x32_bf16 v[120:123], v[160:163], v[184:187], v[120:123]
	v_mfma_f32_16x16x32_bf16 v[116:119], v[152:155], v[192:195], v[116:119]
	v_mfma_f32_16x16x32_bf16 v[108:111], v[160:163], v[192:195], v[108:111]
	v_mfma_f32_16x16x32_bf16 v[100:103], v[152:155], v[200:203], v[100:103]
	v_mfma_f32_16x16x32_bf16 v[92:95], v[160:163], v[200:203], v[92:95]
	v_mfma_f32_16x16x32_bf16 v[84:87], v[152:155], v[208:211], v[84:87]
	v_mfma_f32_16x16x32_bf16 v[76:79], v[160:163], v[208:211], v[76:79]
	v_mfma_f32_16x16x32_bf16 v[124:127], v[156:159], v[188:191], v[124:127]
	v_mfma_f32_16x16x32_bf16 v[120:123], v[164:167], v[188:191], v[120:123]
	v_mfma_f32_16x16x32_bf16 v[116:119], v[156:159], v[196:199], v[116:119]
	v_mfma_f32_16x16x32_bf16 v[108:111], v[164:167], v[196:199], v[108:111]
	v_mfma_f32_16x16x32_bf16 v[100:103], v[156:159], v[204:207], v[100:103]
	v_mfma_f32_16x16x32_bf16 v[92:95], v[164:167], v[204:207], v[92:95]
	v_mfma_f32_16x16x32_bf16 v[84:87], v[156:159], v[212:215], v[84:87]
	v_mfma_f32_16x16x32_bf16 v[76:79], v[164:167], v[212:215], v[76:79]
	v_mfma_f32_16x16x32_bf16 v[112:115], v[168:171], v[184:187], v[112:115]
	v_mfma_f32_16x16x32_bf16 v[104:107], v[176:179], v[184:187], v[104:107]
	v_mfma_f32_16x16x32_bf16 v[96:99], v[168:171], v[192:195], v[96:99]
	v_mfma_f32_16x16x32_bf16 v[88:91], v[176:179], v[192:195], v[88:91]
	v_mfma_f32_16x16x32_bf16 v[80:83], v[168:171], v[200:203], v[80:83]
	v_mfma_f32_16x16x32_bf16 v[72:75], v[176:179], v[200:203], v[72:75]
	v_mfma_f32_16x16x32_bf16 v[68:71], v[168:171], v[208:211], v[68:71]
	v_mfma_f32_16x16x32_bf16 v[64:67], v[176:179], v[208:211], v[64:67]
	v_mfma_f32_16x16x32_bf16 v[112:115], v[172:175], v[188:191], v[112:115]
	v_mfma_f32_16x16x32_bf16 v[104:107], v[180:183], v[188:191], v[104:107]
	v_mfma_f32_16x16x32_bf16 v[96:99], v[172:175], v[196:199], v[96:99]
	v_mfma_f32_16x16x32_bf16 v[88:91], v[180:183], v[196:199], v[88:91]
	v_mfma_f32_16x16x32_bf16 v[80:83], v[172:175], v[204:207], v[80:83]
	v_mfma_f32_16x16x32_bf16 v[72:75], v[180:183], v[204:207], v[72:75]
	v_mfma_f32_16x16x32_bf16 v[68:71], v[172:175], v[212:215], v[68:71]
	v_mfma_f32_16x16x32_bf16 v[64:67], v[180:183], v[212:215], v[64:67]
	s_barrier
	s_setprio 0
	s_add_i32 m0, s25, 0x10000
	ds_read_b128 v[184:187], v151 offset:16384
	ds_read_b128 v[188:191], v151 offset:17408
	ds_read_b128 v[192:195], v151 offset:18432
	ds_read_b128 v[196:199], v151 offset:19456
	global_load_lds_dwordx4 v132, s[40:41]
	s_add_i32 m0, s25, 0x12000
	s_add_u32 s22, s40, 0x2b0000
	s_mov_b64 s[98:99], s[40:41]
	s_addc_u32 s23, s41, 0
	global_load_lds_dwordx4 v128, s[98:99]
	s_add_i32 m0, s25, 0x14000
	ds_read_b128 v[200:203], v151 offset:20480
	global_load_lds_dwordx4 v132, s[22:23]
	s_add_i32 m0, s25, 0x16000
	ds_read_b128 v[204:207], v151 offset:21504
	global_load_lds_dwordx4 v128, s[22:23]
	s_mov_b32 m0, s25
	ds_read_b128 v[208:211], v151 offset:22528
	global_load_lds_dwordx4 v134, s[56:57]
	s_mov_b32 m0, s26
	ds_read_b128 v[212:215], v151 offset:23552
	global_load_lds_dwordx4 v130, s[56:57]
	s_waitcnt vmcnt(8) lgkmcnt(0)
	s_setprio 1
	s_barrier
	v_mfma_f32_16x16x32_bf16 v[60:63], v[152:155], v[184:187], v[60:63]
	v_mfma_f32_16x16x32_bf16 v[56:59], v[160:163], v[184:187], v[56:59]
	v_mfma_f32_16x16x32_bf16 v[52:55], v[152:155], v[192:195], v[52:55]
	v_mfma_f32_16x16x32_bf16 v[44:47], v[160:163], v[192:195], v[44:47]
	v_mfma_f32_16x16x32_bf16 v[36:39], v[152:155], v[200:203], v[36:39]
	v_mfma_f32_16x16x32_bf16 v[28:31], v[160:163], v[200:203], v[28:31]
	v_mfma_f32_16x16x32_bf16 v[20:23], v[152:155], v[208:211], v[20:23]
	v_mfma_f32_16x16x32_bf16 v[12:15], v[160:163], v[208:211], v[12:15]
	v_mfma_f32_16x16x32_bf16 v[60:63], v[156:159], v[188:191], v[60:63]
	v_mfma_f32_16x16x32_bf16 v[56:59], v[164:167], v[188:191], v[56:59]
	v_mfma_f32_16x16x32_bf16 v[52:55], v[156:159], v[196:199], v[52:55]
	v_mfma_f32_16x16x32_bf16 v[44:47], v[164:167], v[196:199], v[44:47]
	v_mfma_f32_16x16x32_bf16 v[36:39], v[156:159], v[204:207], v[36:39]
	v_mfma_f32_16x16x32_bf16 v[28:31], v[164:167], v[204:207], v[28:31]
	v_mfma_f32_16x16x32_bf16 v[20:23], v[156:159], v[212:215], v[20:23]
	v_mfma_f32_16x16x32_bf16 v[12:15], v[164:167], v[212:215], v[12:15]
	v_mfma_f32_16x16x32_bf16 v[48:51], v[168:171], v[184:187], v[48:51]
	v_mfma_f32_16x16x32_bf16 v[40:43], v[176:179], v[184:187], v[40:43]
	v_mfma_f32_16x16x32_bf16 v[32:35], v[168:171], v[192:195], v[32:35]
	v_mfma_f32_16x16x32_bf16 v[24:27], v[176:179], v[192:195], v[24:27]
	v_mfma_f32_16x16x32_bf16 v[16:19], v[168:171], v[200:203], v[16:19]
	v_mfma_f32_16x16x32_bf16 v[8:11], v[176:179], v[200:203], v[8:11]
	v_mfma_f32_16x16x32_bf16 v[4:7], v[168:171], v[208:211], v[4:7]
	v_mfma_f32_16x16x32_bf16 v[0:3], v[176:179], v[208:211], v[0:3]
	v_mfma_f32_16x16x32_bf16 v[48:51], v[172:175], v[188:191], v[48:51]
	v_mfma_f32_16x16x32_bf16 v[40:43], v[180:183], v[188:191], v[40:43]
	v_mfma_f32_16x16x32_bf16 v[32:35], v[172:175], v[196:199], v[32:35]
	v_mfma_f32_16x16x32_bf16 v[24:27], v[180:183], v[196:199], v[24:27]
	v_mfma_f32_16x16x32_bf16 v[16:19], v[172:175], v[204:207], v[16:19]
	v_mfma_f32_16x16x32_bf16 v[8:11], v[180:183], v[204:207], v[8:11]
	v_mfma_f32_16x16x32_bf16 v[4:7], v[172:175], v[212:215], v[4:7]
	v_mfma_f32_16x16x32_bf16 v[0:3], v[180:183], v[212:215], v[0:3]
	s_barrier
	s_setprio 0
	ds_read_b128 v[152:155], v149 offset:32768
	ds_read_b128 v[156:159], v149 offset:33792
	ds_read_b128 v[160:163], v149 offset:34816
	ds_read_b128 v[164:167], v149 offset:35840
	ds_read_b128 v[168:171], v150 offset:32768
	ds_read_b128 v[172:175], v150 offset:33792
	ds_read_b128 v[176:179], v150 offset:34816
	ds_read_b128 v[180:183], v150 offset:35840
	s_add_u32 s22, s56, 0x2b0000
	s_addc_u32 s23, s57, 0
	s_mov_b32 m0, s27
	ds_read_b128 v[184:187], v151 offset:32768
	ds_read_b128 v[188:191], v151 offset:33792
	ds_read_b128 v[192:195], v151 offset:34816
	ds_read_b128 v[196:199], v151 offset:35840
	ds_read_b128 v[200:203], v151 offset:36864
	ds_read_b128 v[204:207], v151 offset:37888
	ds_read_b128 v[208:211], v151 offset:38912
	global_load_lds_dwordx4 v134, s[22:23]
	s_mov_b32 m0, s28
	ds_read_b128 v[212:215], v151 offset:39936
	global_load_lds_dwordx4 v130, s[22:23]
	s_waitcnt vmcnt(8) lgkmcnt(0)
	s_setprio 1
	s_barrier
	v_mfma_f32_16x16x32_bf16 v[124:127], v[152:155], v[184:187], v[124:127]
	v_mfma_f32_16x16x32_bf16 v[120:123], v[160:163], v[184:187], v[120:123]
	v_mfma_f32_16x16x32_bf16 v[116:119], v[152:155], v[192:195], v[116:119]
	v_mfma_f32_16x16x32_bf16 v[108:111], v[160:163], v[192:195], v[108:111]
	v_mfma_f32_16x16x32_bf16 v[100:103], v[152:155], v[200:203], v[100:103]
	v_mfma_f32_16x16x32_bf16 v[92:95], v[160:163], v[200:203], v[92:95]
	v_mfma_f32_16x16x32_bf16 v[84:87], v[152:155], v[208:211], v[84:87]
	v_mfma_f32_16x16x32_bf16 v[76:79], v[160:163], v[208:211], v[76:79]
	v_mfma_f32_16x16x32_bf16 v[124:127], v[156:159], v[188:191], v[124:127]
	v_mfma_f32_16x16x32_bf16 v[120:123], v[164:167], v[188:191], v[120:123]
	v_mfma_f32_16x16x32_bf16 v[116:119], v[156:159], v[196:199], v[116:119]
	v_mfma_f32_16x16x32_bf16 v[108:111], v[164:167], v[196:199], v[108:111]
	v_mfma_f32_16x16x32_bf16 v[100:103], v[156:159], v[204:207], v[100:103]
	v_mfma_f32_16x16x32_bf16 v[92:95], v[164:167], v[204:207], v[92:95]
	v_mfma_f32_16x16x32_bf16 v[84:87], v[156:159], v[212:215], v[84:87]
	v_mfma_f32_16x16x32_bf16 v[76:79], v[164:167], v[212:215], v[76:79]
	v_mfma_f32_16x16x32_bf16 v[112:115], v[168:171], v[184:187], v[112:115]
	v_mfma_f32_16x16x32_bf16 v[104:107], v[176:179], v[184:187], v[104:107]
	v_mfma_f32_16x16x32_bf16 v[96:99], v[168:171], v[192:195], v[96:99]
	v_mfma_f32_16x16x32_bf16 v[88:91], v[176:179], v[192:195], v[88:91]
	v_mfma_f32_16x16x32_bf16 v[80:83], v[168:171], v[200:203], v[80:83]
	v_mfma_f32_16x16x32_bf16 v[72:75], v[176:179], v[200:203], v[72:75]
	v_mfma_f32_16x16x32_bf16 v[68:71], v[168:171], v[208:211], v[68:71]
	v_mfma_f32_16x16x32_bf16 v[64:67], v[176:179], v[208:211], v[64:67]
	v_mfma_f32_16x16x32_bf16 v[112:115], v[172:175], v[188:191], v[112:115]
	v_mfma_f32_16x16x32_bf16 v[104:107], v[180:183], v[188:191], v[104:107]
	v_mfma_f32_16x16x32_bf16 v[96:99], v[172:175], v[196:199], v[96:99]
	v_mfma_f32_16x16x32_bf16 v[88:91], v[180:183], v[196:199], v[88:91]
	v_mfma_f32_16x16x32_bf16 v[80:83], v[172:175], v[204:207], v[80:83]
	v_mfma_f32_16x16x32_bf16 v[72:75], v[180:183], v[204:207], v[72:75]
	v_mfma_f32_16x16x32_bf16 v[68:71], v[172:175], v[212:215], v[68:71]
	v_mfma_f32_16x16x32_bf16 v[64:67], v[180:183], v[212:215], v[64:67]
	s_barrier
	s_setprio 0
	s_add_i32 m0, s25, 0x17f80
	ds_read_b128 v[184:187], v151 offset:49152
	ds_read_b128 v[188:191], v151 offset:50176
	ds_read_b128 v[192:195], v151 offset:51200
	ds_read_b128 v[196:199], v151 offset:52224
	global_load_lds_dwordx4 v132, s[40:41] offset:128
	s_add_i32 m0, s25, 0x19f80
	s_add_u32 s22, s40, 0x2b0080
	s_addc_u32 s23, s41, 0
	global_load_lds_dwordx4 v128, s[98:99] offset:128
	s_add_i32 m0, s25, 0x1c000
	ds_read_b128 v[200:203], v151 offset:53248
	global_load_lds_dwordx4 v132, s[22:23]
	s_add_i32 m0, s25, 0x1e000
	ds_read_b128 v[204:207], v151 offset:54272
	global_load_lds_dwordx4 v128, s[22:23]
	s_add_i32 m0, s31, -128
	ds_read_b128 v[208:211], v151 offset:55296
	global_load_lds_dwordx4 v134, s[56:57] offset:128
	s_add_i32 m0, s33, -128
	ds_read_b128 v[212:215], v151 offset:56320
	global_load_lds_dwordx4 v130, s[56:57] offset:128
	s_waitcnt vmcnt(8) lgkmcnt(0)
	s_setprio 1
	s_barrier
	v_mfma_f32_16x16x32_bf16 v[60:63], v[152:155], v[184:187], v[60:63]
	v_mfma_f32_16x16x32_bf16 v[56:59], v[160:163], v[184:187], v[56:59]
	v_mfma_f32_16x16x32_bf16 v[52:55], v[152:155], v[192:195], v[52:55]
	v_mfma_f32_16x16x32_bf16 v[44:47], v[160:163], v[192:195], v[44:47]
	v_mfma_f32_16x16x32_bf16 v[36:39], v[152:155], v[200:203], v[36:39]
	v_mfma_f32_16x16x32_bf16 v[28:31], v[160:163], v[200:203], v[28:31]
	v_mfma_f32_16x16x32_bf16 v[20:23], v[152:155], v[208:211], v[20:23]
	v_mfma_f32_16x16x32_bf16 v[12:15], v[160:163], v[208:211], v[12:15]
	v_mfma_f32_16x16x32_bf16 v[60:63], v[156:159], v[188:191], v[60:63]
	v_mfma_f32_16x16x32_bf16 v[56:59], v[164:167], v[188:191], v[56:59]
	v_mfma_f32_16x16x32_bf16 v[52:55], v[156:159], v[196:199], v[52:55]
	v_mfma_f32_16x16x32_bf16 v[44:47], v[164:167], v[196:199], v[44:47]
	v_mfma_f32_16x16x32_bf16 v[36:39], v[156:159], v[204:207], v[36:39]
	v_mfma_f32_16x16x32_bf16 v[28:31], v[164:167], v[204:207], v[28:31]
	v_mfma_f32_16x16x32_bf16 v[20:23], v[156:159], v[212:215], v[20:23]
	v_mfma_f32_16x16x32_bf16 v[12:15], v[164:167], v[212:215], v[12:15]
	v_mfma_f32_16x16x32_bf16 v[48:51], v[168:171], v[184:187], v[48:51]
	v_mfma_f32_16x16x32_bf16 v[40:43], v[176:179], v[184:187], v[40:43]
	v_mfma_f32_16x16x32_bf16 v[32:35], v[168:171], v[192:195], v[32:35]
	v_mfma_f32_16x16x32_bf16 v[24:27], v[176:179], v[192:195], v[24:27]
	v_mfma_f32_16x16x32_bf16 v[16:19], v[168:171], v[200:203], v[16:19]
	v_mfma_f32_16x16x32_bf16 v[8:11], v[176:179], v[200:203], v[8:11]
	v_mfma_f32_16x16x32_bf16 v[4:7], v[168:171], v[208:211], v[4:7]
	v_mfma_f32_16x16x32_bf16 v[0:3], v[176:179], v[208:211], v[0:3]
	v_mfma_f32_16x16x32_bf16 v[48:51], v[172:175], v[188:191], v[48:51]
	v_mfma_f32_16x16x32_bf16 v[40:43], v[180:183], v[188:191], v[40:43]
	v_mfma_f32_16x16x32_bf16 v[32:35], v[172:175], v[196:199], v[32:35]
	v_mfma_f32_16x16x32_bf16 v[24:27], v[180:183], v[196:199], v[24:27]
	v_mfma_f32_16x16x32_bf16 v[16:19], v[172:175], v[204:207], v[16:19]
	v_mfma_f32_16x16x32_bf16 v[8:11], v[180:183], v[204:207], v[8:11]
	v_mfma_f32_16x16x32_bf16 v[4:7], v[172:175], v[212:215], v[4:7]
	v_mfma_f32_16x16x32_bf16 v[0:3], v[180:183], v[212:215], v[0:3]
	s_barrier
	s_setprio 0
	s_add_i32 s62, s62, 2
	s_add_u32 s60, s60, 0x100
	s_addc_u32 s61, s61, 0
	s_cmpk_gt_u32 s62, 0xa9
	s_mov_b64 s[22:23], s[36:37]
	s_cbranch_scc0 .LBB0_258
	s_and_b64 vcc, exec, s[14:15]
	s_cbranch_vccz .LBB0_261
	s_barrier

.LBB0_394:
	ds_read_b128 v[156:159], v152
	ds_read_b128 v[160:163], v152 offset:1024
	ds_read_b128 v[164:167], v152 offset:2048
	ds_read_b128 v[168:171], v152 offset:3072
	ds_read_b128 v[172:175], v153
	ds_read_b128 v[176:179], v153 offset:1024
	ds_read_b128 v[180:183], v153 offset:2048
	ds_read_b128 v[184:187], v153 offset:3072
	s_add_u32 s40, s38, 0xfff00080
	s_addc_u32 s41, s39, -1
	s_cmp_eq_u32 s64, 60
	s_cselect_b32 s57, s21, s41
	s_cselect_b32 s56, s60, s40
	s_cselect_b32 s41, s15, s63
	s_cselect_b32 s40, s61, s62
	s_add_i32 m0, s29, 0xc000
	ds_read_b128 v[188:191], v154
	ds_read_b128 v[192:195], v154 offset:1024
	ds_read_b128 v[196:199], v154 offset:2048
	ds_read_b128 v[200:203], v154 offset:3072
	ds_read_b128 v[204:207], v154 offset:4096
	ds_read_b128 v[208:211], v154 offset:5120
	ds_read_b128 v[212:215], v154 offset:6144
	global_load_lds_dwordx4 v140, s[38:39]
	s_add_i32 m0, s29, 0xe000
	ds_read_b128 v[216:219], v154 offset:7168
	global_load_lds_dwordx4 v142, s[38:39]
	s_waitcnt vmcnt(8) lgkmcnt(0)
	s_setprio 1
	s_barrier
	v_mfma_f32_16x16x32_bf16 v[124:127], v[156:159], v[188:191], v[124:127]
	v_mfma_f32_16x16x32_bf16 v[120:123], v[164:167], v[188:191], v[120:123]
	v_mfma_f32_16x16x32_bf16 v[112:115], v[156:159], v[196:199], v[112:115]
	v_mfma_f32_16x16x32_bf16 v[104:107], v[164:167], v[196:199], v[104:107]
	v_mfma_f32_16x16x32_bf16 v[96:99], v[156:159], v[204:207], v[96:99]
	v_mfma_f32_16x16x32_bf16 v[88:91], v[164:167], v[204:207], v[88:91]
	v_mfma_f32_16x16x32_bf16 v[80:83], v[156:159], v[212:215], v[80:83]
	v_mfma_f32_16x16x32_bf16 v[72:75], v[164:167], v[212:215], v[72:75]
	v_mfma_f32_16x16x32_bf16 v[124:127], v[160:163], v[192:195], v[124:127]
	v_mfma_f32_16x16x32_bf16 v[120:123], v[168:171], v[192:195], v[120:123]
	v_mfma_f32_16x16x32_bf16 v[112:115], v[160:163], v[200:203], v[112:115]
	v_mfma_f32_16x16x32_bf16 v[104:107], v[168:171], v[200:203], v[104:107]
	v_mfma_f32_16x16x32_bf16 v[96:99], v[160:163], v[208:211], v[96:99]
	v_mfma_f32_16x16x32_bf16 v[88:91], v[168:171], v[208:211], v[88:91]
	v_mfma_f32_16x16x32_bf16 v[80:83], v[160:163], v[216:219], v[80:83]
	v_mfma_f32_16x16x32_bf16 v[72:75], v[168:171], v[216:219], v[72:75]
	v_mfma_f32_16x16x32_bf16 v[116:119], v[172:175], v[188:191], v[116:119]
	v_mfma_f32_16x16x32_bf16 v[108:111], v[180:183], v[188:191], v[108:111]
	v_mfma_f32_16x16x32_bf16 v[100:103], v[172:175], v[196:199], v[100:103]
	v_mfma_f32_16x16x32_bf16 v[92:95], v[180:183], v[196:199], v[92:95]
	v_mfma_f32_16x16x32_bf16 v[84:87], v[172:175], v[204:207], v[84:87]
	v_mfma_f32_16x16x32_bf16 v[76:79], v[180:183], v[204:207], v[76:79]
	v_mfma_f32_16x16x32_bf16 v[68:71], v[172:175], v[212:215], v[68:71]
	v_mfma_f32_16x16x32_bf16 v[64:67], v[180:183], v[212:215], v[64:67]
	v_mfma_f32_16x16x32_bf16 v[116:119], v[176:179], v[192:195], v[116:119]
	v_mfma_f32_16x16x32_bf16 v[108:111], v[184:187], v[192:195], v[108:111]
	v_mfma_f32_16x16x32_bf16 v[100:103], v[176:179], v[200:203], v[100:103]
	v_mfma_f32_16x16x32_bf16 v[92:95], v[184:187], v[200:203], v[92:95]
	v_mfma_f32_16x16x32_bf16 v[84:87], v[176:179], v[208:211], v[84:87]
	v_mfma_f32_16x16x32_bf16 v[76:79], v[184:187], v[208:211], v[76:79]
	v_mfma_f32_16x16x32_bf16 v[68:71], v[176:179], v[216:219], v[68:71]
	v_mfma_f32_16x16x32_bf16 v[64:67], v[184:187], v[216:219], v[64:67]
	s_barrier
	s_setprio 0
	s_add_i32 m0, s29, 0x10000
	ds_read_b128 v[188:191], v154 offset:16384
	ds_read_b128 v[192:195], v154 offset:17408
	ds_read_b128 v[196:199], v154 offset:18432
	ds_read_b128 v[200:203], v154 offset:19456
	ds_read_b128 v[204:207], v154 offset:20480
	global_load_lds_dwordx4 v132, s[40:41]
	s_add_i32 m0, s29, 0x12000
	s_add_u32 s66, s40, 0x100000
	s_mov_b64 s[98:99], s[40:41]
	s_addc_u32 s67, s41, 0
	global_load_lds_dwordx4 v128, s[98:99]
	s_add_i32 m0, s29, 0x14000
	s_mov_b64 s[100:101], s[56:57]
	global_load_lds_dwordx4 v132, s[66:67]
	s_add_i32 m0, s29, 0x16000
	ds_read_b128 v[208:211], v154 offset:21504
	global_load_lds_dwordx4 v128, s[66:67]
	s_mov_b64 s[100:101], s[56:57]
	s_mov_b32 m0, s29
	ds_read_b128 v[212:215], v154 offset:22528
	global_load_lds_dwordx4 v134, s[100:101]
	s_mov_b32 m0, s30
	ds_read_b128 v[216:219], v154 offset:23552
	global_load_lds_dwordx4 v130, s[100:101]
	s_waitcnt vmcnt(8) lgkmcnt(0)
	s_setprio 1
	s_barrier
	v_mfma_f32_16x16x32_bf16 v[60:63], v[156:159], v[188:191], v[60:63]
	v_mfma_f32_16x16x32_bf16 v[56:59], v[164:167], v[188:191], v[56:59]
	v_mfma_f32_16x16x32_bf16 v[52:55], v[156:159], v[196:199], v[52:55]
	v_mfma_f32_16x16x32_bf16 v[44:47], v[164:167], v[196:199], v[44:47]
	v_mfma_f32_16x16x32_bf16 v[36:39], v[156:159], v[204:207], v[36:39]
	v_mfma_f32_16x16x32_bf16 v[28:31], v[164:167], v[204:207], v[28:31]
	v_mfma_f32_16x16x32_bf16 v[20:23], v[156:159], v[212:215], v[20:23]
	v_mfma_f32_16x16x32_bf16 v[12:15], v[164:167], v[212:215], v[12:15]
	v_mfma_f32_16x16x32_bf16 v[60:63], v[160:163], v[192:195], v[60:63]
	v_mfma_f32_16x16x32_bf16 v[56:59], v[168:171], v[192:195], v[56:59]
	v_mfma_f32_16x16x32_bf16 v[52:55], v[160:163], v[200:203], v[52:55]
	v_mfma_f32_16x16x32_bf16 v[44:47], v[168:171], v[200:203], v[44:47]
	v_mfma_f32_16x16x32_bf16 v[36:39], v[160:163], v[208:211], v[36:39]
	v_mfma_f32_16x16x32_bf16 v[28:31], v[168:171], v[208:211], v[28:31]
	v_mfma_f32_16x16x32_bf16 v[20:23], v[160:163], v[216:219], v[20:23]
	v_mfma_f32_16x16x32_bf16 v[12:15], v[168:171], v[216:219], v[12:15]
	v_mfma_f32_16x16x32_bf16 v[48:51], v[172:175], v[188:191], v[48:51]
	v_mfma_f32_16x16x32_bf16 v[40:43], v[180:183], v[188:191], v[40:43]
	v_mfma_f32_16x16x32_bf16 v[32:35], v[172:175], v[196:199], v[32:35]
	v_mfma_f32_16x16x32_bf16 v[24:27], v[180:183], v[196:199], v[24:27]
	v_mfma_f32_16x16x32_bf16 v[16:19], v[172:175], v[204:207], v[16:19]
	v_mfma_f32_16x16x32_bf16 v[8:11], v[180:183], v[204:207], v[8:11]
	v_mfma_f32_16x16x32_bf16 v[4:7], v[172:175], v[212:215], v[4:7]
	v_mfma_f32_16x16x32_bf16 v[0:3], v[180:183], v[212:215], v[0:3]
	v_mfma_f32_16x16x32_bf16 v[48:51], v[176:179], v[192:195], v[48:51]
	v_mfma_f32_16x16x32_bf16 v[40:43], v[184:187], v[192:195], v[40:43]
	v_mfma_f32_16x16x32_bf16 v[32:35], v[176:179], v[200:203], v[32:35]
	v_mfma_f32_16x16x32_bf16 v[24:27], v[184:187], v[200:203], v[24:27]
	v_mfma_f32_16x16x32_bf16 v[16:19], v[176:179], v[208:211], v[16:19]
	v_mfma_f32_16x16x32_bf16 v[8:11], v[184:187], v[208:211], v[8:11]
	v_mfma_f32_16x16x32_bf16 v[4:7], v[176:179], v[216:219], v[4:7]
	v_mfma_f32_16x16x32_bf16 v[0:3], v[184:187], v[216:219], v[0:3]
	s_barrier
	s_setprio 0
	ds_read_b128 v[156:159], v152 offset:32768
	ds_read_b128 v[160:163], v152 offset:33792
	ds_read_b128 v[164:167], v152 offset:34816
	ds_read_b128 v[168:171], v152 offset:35840
	ds_read_b128 v[172:175], v153 offset:32768
	ds_read_b128 v[176:179], v153 offset:33792
	ds_read_b128 v[180:183], v153 offset:34816
	ds_read_b128 v[184:187], v153 offset:35840
	s_add_u32 s56, s56, 0x100000
	s_addc_u32 s57, s57, 0
	s_mov_b32 m0, s31
	ds_read_b128 v[188:191], v154 offset:32768
	ds_read_b128 v[192:195], v154 offset:33792
	ds_read_b128 v[196:199], v154 offset:34816
	ds_read_b128 v[200:203], v154 offset:35840
	ds_read_b128 v[204:207], v154 offset:36864
	ds_read_b128 v[208:211], v154 offset:37888
	ds_read_b128 v[212:215], v154 offset:38912
	global_load_lds_dwordx4 v134, s[56:57]
	s_mov_b32 m0, s33
	ds_read_b128 v[216:219], v154 offset:39936
	global_load_lds_dwordx4 v130, s[56:57]
	s_waitcnt vmcnt(8) lgkmcnt(0)
	s_setprio 1
	s_barrier
	v_mfma_f32_16x16x32_bf16 v[124:127], v[156:159], v[188:191], v[124:127]
	v_mfma_f32_16x16x32_bf16 v[120:123], v[164:167], v[188:191], v[120:123]
	v_mfma_f32_16x16x32_bf16 v[112:115], v[156:159], v[196:199], v[112:115]
	v_mfma_f32_16x16x32_bf16 v[104:107], v[164:167], v[196:199], v[104:107]
	v_mfma_f32_16x16x32_bf16 v[96:99], v[156:159], v[204:207], v[96:99]
	v_mfma_f32_16x16x32_bf16 v[88:91], v[164:167], v[204:207], v[88:91]
	v_mfma_f32_16x16x32_bf16 v[80:83], v[156:159], v[212:215], v[80:83]
	v_mfma_f32_16x16x32_bf16 v[72:75], v[164:167], v[212:215], v[72:75]
	v_mfma_f32_16x16x32_bf16 v[124:127], v[160:163], v[192:195], v[124:127]
	v_mfma_f32_16x16x32_bf16 v[120:123], v[168:171], v[192:195], v[120:123]
	v_mfma_f32_16x16x32_bf16 v[112:115], v[160:163], v[200:203], v[112:115]
	v_mfma_f32_16x16x32_bf16 v[104:107], v[168:171], v[200:203], v[104:107]
	v_mfma_f32_16x16x32_bf16 v[96:99], v[160:163], v[208:211], v[96:99]
	v_mfma_f32_16x16x32_bf16 v[88:91], v[168:171], v[208:211], v[88:91]
	v_mfma_f32_16x16x32_bf16 v[80:83], v[160:163], v[216:219], v[80:83]
	v_mfma_f32_16x16x32_bf16 v[72:75], v[168:171], v[216:219], v[72:75]
	v_mfma_f32_16x16x32_bf16 v[116:119], v[172:175], v[188:191], v[116:119]
	v_mfma_f32_16x16x32_bf16 v[108:111], v[180:183], v[188:191], v[108:111]
	v_mfma_f32_16x16x32_bf16 v[100:103], v[172:175], v[196:199], v[100:103]
	v_mfma_f32_16x16x32_bf16 v[92:95], v[180:183], v[196:199], v[92:95]
	v_mfma_f32_16x16x32_bf16 v[84:87], v[172:175], v[204:207], v[84:87]
	v_mfma_f32_16x16x32_bf16 v[76:79], v[180:183], v[204:207], v[76:79]
	v_mfma_f32_16x16x32_bf16 v[68:71], v[172:175], v[212:215], v[68:71]
	v_mfma_f32_16x16x32_bf16 v[64:67], v[180:183], v[212:215], v[64:67]
	v_mfma_f32_16x16x32_bf16 v[116:119], v[176:179], v[192:195], v[116:119]
	v_mfma_f32_16x16x32_bf16 v[108:111], v[184:187], v[192:195], v[108:111]
	v_mfma_f32_16x16x32_bf16 v[100:103], v[176:179], v[200:203], v[100:103]
	v_mfma_f32_16x16x32_bf16 v[92:95], v[184:187], v[200:203], v[92:95]
	v_mfma_f32_16x16x32_bf16 v[84:87], v[176:179], v[208:211], v[84:87]
	v_mfma_f32_16x16x32_bf16 v[76:79], v[184:187], v[208:211], v[76:79]
	v_mfma_f32_16x16x32_bf16 v[68:71], v[176:179], v[216:219], v[68:71]
	v_mfma_f32_16x16x32_bf16 v[64:67], v[184:187], v[216:219], v[64:67]
	s_barrier
	s_setprio 0
	s_add_i32 m0, s29, 0x17f80
	ds_read_b128 v[188:191], v154 offset:49152
	ds_read_b128 v[192:195], v154 offset:50176
	ds_read_b128 v[196:199], v154 offset:51200
	ds_read_b128 v[200:203], v154 offset:52224
	global_load_lds_dwordx4 v132, s[40:41] offset:128
	s_add_i32 m0, s29, 0x19f80
	s_add_u32 s40, s40, 0x100080
	s_addc_u32 s41, s41, 0
	global_load_lds_dwordx4 v128, s[98:99] offset:128
	s_add_i32 m0, s29, 0x1c000
	ds_read_b128 v[204:207], v154 offset:53248
	global_load_lds_dwordx4 v132, s[40:41]
	s_add_i32 m0, s29, 0x1e000
	ds_read_b128 v[208:211], v154 offset:54272
	global_load_lds_dwordx4 v128, s[40:41]
	s_add_i32 m0, s54, -128
	ds_read_b128 v[212:215], v154 offset:55296
	global_load_lds_dwordx4 v134, s[100:101] offset:128
	s_add_i32 m0, s55, -128
	ds_read_b128 v[216:219], v154 offset:56320
	global_load_lds_dwordx4 v130, s[100:101] offset:128
	s_waitcnt vmcnt(8) lgkmcnt(0)
	s_setprio 1
	s_barrier
	v_mfma_f32_16x16x32_bf16 v[60:63], v[156:159], v[188:191], v[60:63]
	v_mfma_f32_16x16x32_bf16 v[56:59], v[164:167], v[188:191], v[56:59]
	v_mfma_f32_16x16x32_bf16 v[52:55], v[156:159], v[196:199], v[52:55]
	v_mfma_f32_16x16x32_bf16 v[44:47], v[164:167], v[196:199], v[44:47]
	v_mfma_f32_16x16x32_bf16 v[36:39], v[156:159], v[204:207], v[36:39]
	v_mfma_f32_16x16x32_bf16 v[28:31], v[164:167], v[204:207], v[28:31]
	v_mfma_f32_16x16x32_bf16 v[20:23], v[156:159], v[212:215], v[20:23]
	v_mfma_f32_16x16x32_bf16 v[12:15], v[164:167], v[212:215], v[12:15]
	v_mfma_f32_16x16x32_bf16 v[60:63], v[160:163], v[192:195], v[60:63]
	v_mfma_f32_16x16x32_bf16 v[56:59], v[168:171], v[192:195], v[56:59]
	v_mfma_f32_16x16x32_bf16 v[52:55], v[160:163], v[200:203], v[52:55]
	v_mfma_f32_16x16x32_bf16 v[44:47], v[168:171], v[200:203], v[44:47]
	v_mfma_f32_16x16x32_bf16 v[36:39], v[160:163], v[208:211], v[36:39]
	v_mfma_f32_16x16x32_bf16 v[28:31], v[168:171], v[208:211], v[28:31]
	v_mfma_f32_16x16x32_bf16 v[20:23], v[160:163], v[216:219], v[20:23]
	v_mfma_f32_16x16x32_bf16 v[12:15], v[168:171], v[216:219], v[12:15]
	v_mfma_f32_16x16x32_bf16 v[48:51], v[172:175], v[188:191], v[48:51]
	v_mfma_f32_16x16x32_bf16 v[40:43], v[180:183], v[188:191], v[40:43]
	v_mfma_f32_16x16x32_bf16 v[32:35], v[172:175], v[196:199], v[32:35]
	v_mfma_f32_16x16x32_bf16 v[24:27], v[180:183], v[196:199], v[24:27]
	v_mfma_f32_16x16x32_bf16 v[16:19], v[172:175], v[204:207], v[16:19]
	v_mfma_f32_16x16x32_bf16 v[8:11], v[180:183], v[204:207], v[8:11]
	v_mfma_f32_16x16x32_bf16 v[4:7], v[172:175], v[212:215], v[4:7]
	v_mfma_f32_16x16x32_bf16 v[0:3], v[180:183], v[212:215], v[0:3]
	v_mfma_f32_16x16x32_bf16 v[48:51], v[176:179], v[192:195], v[48:51]
	v_mfma_f32_16x16x32_bf16 v[40:43], v[184:187], v[192:195], v[40:43]
	v_mfma_f32_16x16x32_bf16 v[32:35], v[176:179], v[200:203], v[32:35]
	v_mfma_f32_16x16x32_bf16 v[24:27], v[184:187], v[200:203], v[24:27]
	v_mfma_f32_16x16x32_bf16 v[16:19], v[176:179], v[208:211], v[16:19]
	v_mfma_f32_16x16x32_bf16 v[8:11], v[184:187], v[208:211], v[8:11]
	v_mfma_f32_16x16x32_bf16 v[4:7], v[176:179], v[216:219], v[4:7]
	v_mfma_f32_16x16x32_bf16 v[0:3], v[184:187], v[216:219], v[0:3]
	s_barrier
	s_setprio 0
	s_add_i32 s64, s64, 2
	s_add_u32 s38, s38, 0x100
	s_addc_u32 s39, s39, 0
	s_add_u32 s62, s62, 0x100
	s_addc_u32 s63, s63, 0
	s_cmp_gt_u32 s64, 61
	s_cbranch_scc0 .LBB0_394
	s_and_b64 vcc, exec, s[12:13]
	s_cbranch_vccz .LBB0_397
	s_barrier

.LBB0_622:
	ds_read_b128 v[152:155], v149
	ds_read_b128 v[156:159], v149 offset:1024
	ds_read_b128 v[160:163], v149 offset:2048
	ds_read_b128 v[164:167], v149 offset:3072
	ds_read_b128 v[168:171], v150
	ds_read_b128 v[172:175], v150 offset:1024
	ds_read_b128 v[176:179], v150 offset:2048
	ds_read_b128 v[180:183], v150 offset:3072
	s_add_u32 s42, s40, 0xfff00080
	s_addc_u32 s43, s41, -1
	s_cmp_eq_u32 s61, 60
	s_cselect_b32 s45, s25, s43
	s_cselect_b32 s44, s57, s42
	s_cselect_b32 s43, s23, s60
	s_cselect_b32 s42, s58, s59
	s_add_i32 m0, s31, 0xc000
	ds_read_b128 v[184:187], v151
	ds_read_b128 v[188:191], v151 offset:1024
	ds_read_b128 v[192:195], v151 offset:2048
	ds_read_b128 v[196:199], v151 offset:3072
	ds_read_b128 v[200:203], v151 offset:4096
	ds_read_b128 v[204:207], v151 offset:5120
	ds_read_b128 v[208:211], v151 offset:6144
	global_load_lds_dwordx4 v136, s[40:41]
	s_add_i32 m0, s31, 0xe000
	ds_read_b128 v[212:215], v151 offset:7168
	global_load_lds_dwordx4 v138, s[40:41]
	s_waitcnt vmcnt(8) lgkmcnt(0)
	s_setprio 1
	s_barrier
	v_mfma_f32_16x16x32_bf16 v[124:127], v[152:155], v[184:187], v[124:127]
	v_mfma_f32_16x16x32_bf16 v[120:123], v[160:163], v[184:187], v[120:123]
	v_mfma_f32_16x16x32_bf16 v[116:119], v[152:155], v[192:195], v[116:119]
	v_mfma_f32_16x16x32_bf16 v[108:111], v[160:163], v[192:195], v[108:111]
	v_mfma_f32_16x16x32_bf16 v[100:103], v[152:155], v[200:203], v[100:103]
	v_mfma_f32_16x16x32_bf16 v[92:95], v[160:163], v[200:203], v[92:95]
	v_mfma_f32_16x16x32_bf16 v[84:87], v[152:155], v[208:211], v[84:87]
	v_mfma_f32_16x16x32_bf16 v[76:79], v[160:163], v[208:211], v[76:79]
	v_mfma_f32_16x16x32_bf16 v[124:127], v[156:159], v[188:191], v[124:127]
	v_mfma_f32_16x16x32_bf16 v[120:123], v[164:167], v[188:191], v[120:123]
	v_mfma_f32_16x16x32_bf16 v[116:119], v[156:159], v[196:199], v[116:119]
	v_mfma_f32_16x16x32_bf16 v[108:111], v[164:167], v[196:199], v[108:111]
	v_mfma_f32_16x16x32_bf16 v[100:103], v[156:159], v[204:207], v[100:103]
	v_mfma_f32_16x16x32_bf16 v[92:95], v[164:167], v[204:207], v[92:95]
	v_mfma_f32_16x16x32_bf16 v[84:87], v[156:159], v[212:215], v[84:87]
	v_mfma_f32_16x16x32_bf16 v[76:79], v[164:167], v[212:215], v[76:79]
	v_mfma_f32_16x16x32_bf16 v[112:115], v[168:171], v[184:187], v[112:115]
	v_mfma_f32_16x16x32_bf16 v[104:107], v[176:179], v[184:187], v[104:107]
	v_mfma_f32_16x16x32_bf16 v[96:99], v[168:171], v[192:195], v[96:99]
	v_mfma_f32_16x16x32_bf16 v[88:91], v[176:179], v[192:195], v[88:91]
	v_mfma_f32_16x16x32_bf16 v[80:83], v[168:171], v[200:203], v[80:83]
	v_mfma_f32_16x16x32_bf16 v[72:75], v[176:179], v[200:203], v[72:75]
	v_mfma_f32_16x16x32_bf16 v[68:71], v[168:171], v[208:211], v[68:71]
	v_mfma_f32_16x16x32_bf16 v[64:67], v[176:179], v[208:211], v[64:67]
	v_mfma_f32_16x16x32_bf16 v[112:115], v[172:175], v[188:191], v[112:115]
	v_mfma_f32_16x16x32_bf16 v[104:107], v[180:183], v[188:191], v[104:107]
	v_mfma_f32_16x16x32_bf16 v[96:99], v[172:175], v[196:199], v[96:99]
	v_mfma_f32_16x16x32_bf16 v[88:91], v[180:183], v[196:199], v[88:91]
	v_mfma_f32_16x16x32_bf16 v[80:83], v[172:175], v[204:207], v[80:83]
	v_mfma_f32_16x16x32_bf16 v[72:75], v[180:183], v[204:207], v[72:75]
	v_mfma_f32_16x16x32_bf16 v[68:71], v[172:175], v[212:215], v[68:71]
	v_mfma_f32_16x16x32_bf16 v[64:67], v[180:183], v[212:215], v[64:67]
	s_barrier
	s_setprio 0
	s_add_i32 m0, s31, 0x10000
	ds_read_b128 v[184:187], v151 offset:16384
	ds_read_b128 v[188:191], v151 offset:17408
	ds_read_b128 v[192:195], v151 offset:18432
	ds_read_b128 v[196:199], v151 offset:19456
	ds_read_b128 v[200:203], v151 offset:20480
	global_load_lds_dwordx4 v132, s[42:43]
	s_add_i32 m0, s31, 0x12000
	s_add_u32 s62, s42, 0x100000
	s_mov_b64 s[98:99], s[42:43]
	s_addc_u32 s63, s43, 0
	global_load_lds_dwordx4 v128, s[98:99]
	s_add_i32 m0, s31, 0x14000
	s_mov_b64 s[100:101], s[44:45]
	global_load_lds_dwordx4 v132, s[62:63]
	s_add_i32 m0, s31, 0x16000
	ds_read_b128 v[204:207], v151 offset:21504
	global_load_lds_dwordx4 v128, s[62:63]
	s_mov_b64 s[100:101], s[44:45]
	s_mov_b32 m0, s31
	ds_read_b128 v[208:211], v151 offset:22528
	global_load_lds_dwordx4 v134, s[100:101]
	s_mov_b32 m0, s33
	ds_read_b128 v[212:215], v151 offset:23552
	global_load_lds_dwordx4 v130, s[100:101]
	s_waitcnt vmcnt(8) lgkmcnt(0)
	s_setprio 1
	s_barrier
	v_mfma_f32_16x16x32_bf16 v[60:63], v[152:155], v[184:187], v[60:63]
	v_mfma_f32_16x16x32_bf16 v[56:59], v[160:163], v[184:187], v[56:59]
	v_mfma_f32_16x16x32_bf16 v[52:55], v[152:155], v[192:195], v[52:55]
	v_mfma_f32_16x16x32_bf16 v[44:47], v[160:163], v[192:195], v[44:47]
	v_mfma_f32_16x16x32_bf16 v[36:39], v[152:155], v[200:203], v[36:39]
	v_mfma_f32_16x16x32_bf16 v[28:31], v[160:163], v[200:203], v[28:31]
	v_mfma_f32_16x16x32_bf16 v[20:23], v[152:155], v[208:211], v[20:23]
	v_mfma_f32_16x16x32_bf16 v[12:15], v[160:163], v[208:211], v[12:15]
	v_mfma_f32_16x16x32_bf16 v[60:63], v[156:159], v[188:191], v[60:63]
	v_mfma_f32_16x16x32_bf16 v[56:59], v[164:167], v[188:191], v[56:59]
	v_mfma_f32_16x16x32_bf16 v[52:55], v[156:159], v[196:199], v[52:55]
	v_mfma_f32_16x16x32_bf16 v[44:47], v[164:167], v[196:199], v[44:47]
	v_mfma_f32_16x16x32_bf16 v[36:39], v[156:159], v[204:207], v[36:39]
	v_mfma_f32_16x16x32_bf16 v[28:31], v[164:167], v[204:207], v[28:31]
	v_mfma_f32_16x16x32_bf16 v[20:23], v[156:159], v[212:215], v[20:23]
	v_mfma_f32_16x16x32_bf16 v[12:15], v[164:167], v[212:215], v[12:15]
	v_mfma_f32_16x16x32_bf16 v[48:51], v[168:171], v[184:187], v[48:51]
	v_mfma_f32_16x16x32_bf16 v[40:43], v[176:179], v[184:187], v[40:43]
	v_mfma_f32_16x16x32_bf16 v[32:35], v[168:171], v[192:195], v[32:35]
	v_mfma_f32_16x16x32_bf16 v[24:27], v[176:179], v[192:195], v[24:27]
	v_mfma_f32_16x16x32_bf16 v[16:19], v[168:171], v[200:203], v[16:19]
	v_mfma_f32_16x16x32_bf16 v[8:11], v[176:179], v[200:203], v[8:11]
	v_mfma_f32_16x16x32_bf16 v[4:7], v[168:171], v[208:211], v[4:7]
	v_mfma_f32_16x16x32_bf16 v[0:3], v[176:179], v[208:211], v[0:3]
	v_mfma_f32_16x16x32_bf16 v[48:51], v[172:175], v[188:191], v[48:51]
	v_mfma_f32_16x16x32_bf16 v[40:43], v[180:183], v[188:191], v[40:43]
	v_mfma_f32_16x16x32_bf16 v[32:35], v[172:175], v[196:199], v[32:35]
	v_mfma_f32_16x16x32_bf16 v[24:27], v[180:183], v[196:199], v[24:27]
	v_mfma_f32_16x16x32_bf16 v[16:19], v[172:175], v[204:207], v[16:19]
	v_mfma_f32_16x16x32_bf16 v[8:11], v[180:183], v[204:207], v[8:11]
	v_mfma_f32_16x16x32_bf16 v[4:7], v[172:175], v[212:215], v[4:7]
	v_mfma_f32_16x16x32_bf16 v[0:3], v[180:183], v[212:215], v[0:3]
	s_barrier
	s_setprio 0
	ds_read_b128 v[152:155], v149 offset:32768
	ds_read_b128 v[156:159], v149 offset:33792
	ds_read_b128 v[160:163], v149 offset:34816
	ds_read_b128 v[164:167], v149 offset:35840
	ds_read_b128 v[168:171], v150 offset:32768
	ds_read_b128 v[172:175], v150 offset:33792
	ds_read_b128 v[176:179], v150 offset:34816
	ds_read_b128 v[180:183], v150 offset:35840
	s_add_u32 s44, s44, 0x100000
	s_addc_u32 s45, s45, 0
	s_mov_b32 m0, s35
	ds_read_b128 v[184:187], v151 offset:32768
	ds_read_b128 v[188:191], v151 offset:33792
	ds_read_b128 v[192:195], v151 offset:34816
	ds_read_b128 v[196:199], v151 offset:35840
	ds_read_b128 v[200:203], v151 offset:36864
	ds_read_b128 v[204:207], v151 offset:37888
	ds_read_b128 v[208:211], v151 offset:38912
	global_load_lds_dwordx4 v134, s[44:45]
	s_mov_b32 m0, s39
	ds_read_b128 v[212:215], v151 offset:39936
	global_load_lds_dwordx4 v130, s[44:45]
	s_waitcnt vmcnt(8) lgkmcnt(0)
	s_setprio 1
	s_barrier
	v_mfma_f32_16x16x32_bf16 v[124:127], v[152:155], v[184:187], v[124:127]
	v_mfma_f32_16x16x32_bf16 v[120:123], v[160:163], v[184:187], v[120:123]
	v_mfma_f32_16x16x32_bf16 v[116:119], v[152:155], v[192:195], v[116:119]
	v_mfma_f32_16x16x32_bf16 v[108:111], v[160:163], v[192:195], v[108:111]
	v_mfma_f32_16x16x32_bf16 v[100:103], v[152:155], v[200:203], v[100:103]
	v_mfma_f32_16x16x32_bf16 v[92:95], v[160:163], v[200:203], v[92:95]
	v_mfma_f32_16x16x32_bf16 v[84:87], v[152:155], v[208:211], v[84:87]
	v_mfma_f32_16x16x32_bf16 v[76:79], v[160:163], v[208:211], v[76:79]
	v_mfma_f32_16x16x32_bf16 v[124:127], v[156:159], v[188:191], v[124:127]
	v_mfma_f32_16x16x32_bf16 v[120:123], v[164:167], v[188:191], v[120:123]
	v_mfma_f32_16x16x32_bf16 v[116:119], v[156:159], v[196:199], v[116:119]
	v_mfma_f32_16x16x32_bf16 v[108:111], v[164:167], v[196:199], v[108:111]
	v_mfma_f32_16x16x32_bf16 v[100:103], v[156:159], v[204:207], v[100:103]
	v_mfma_f32_16x16x32_bf16 v[92:95], v[164:167], v[204:207], v[92:95]
	v_mfma_f32_16x16x32_bf16 v[84:87], v[156:159], v[212:215], v[84:87]
	v_mfma_f32_16x16x32_bf16 v[76:79], v[164:167], v[212:215], v[76:79]
	v_mfma_f32_16x16x32_bf16 v[112:115], v[168:171], v[184:187], v[112:115]
	v_mfma_f32_16x16x32_bf16 v[104:107], v[176:179], v[184:187], v[104:107]
	v_mfma_f32_16x16x32_bf16 v[96:99], v[168:171], v[192:195], v[96:99]
	v_mfma_f32_16x16x32_bf16 v[88:91], v[176:179], v[192:195], v[88:91]
	v_mfma_f32_16x16x32_bf16 v[80:83], v[168:171], v[200:203], v[80:83]
	v_mfma_f32_16x16x32_bf16 v[72:75], v[176:179], v[200:203], v[72:75]
	v_mfma_f32_16x16x32_bf16 v[68:71], v[168:171], v[208:211], v[68:71]
	v_mfma_f32_16x16x32_bf16 v[64:67], v[176:179], v[208:211], v[64:67]
	v_mfma_f32_16x16x32_bf16 v[112:115], v[172:175], v[188:191], v[112:115]
	v_mfma_f32_16x16x32_bf16 v[104:107], v[180:183], v[188:191], v[104:107]
	v_mfma_f32_16x16x32_bf16 v[96:99], v[172:175], v[196:199], v[96:99]
	v_mfma_f32_16x16x32_bf16 v[88:91], v[180:183], v[196:199], v[88:91]
	v_mfma_f32_16x16x32_bf16 v[80:83], v[172:175], v[204:207], v[80:83]
	v_mfma_f32_16x16x32_bf16 v[72:75], v[180:183], v[204:207], v[72:75]
	v_mfma_f32_16x16x32_bf16 v[68:71], v[172:175], v[212:215], v[68:71]
	v_mfma_f32_16x16x32_bf16 v[64:67], v[180:183], v[212:215], v[64:67]
	s_barrier
	s_setprio 0
	s_add_i32 m0, s31, 0x17f80
	ds_read_b128 v[184:187], v151 offset:49152
	ds_read_b128 v[188:191], v151 offset:50176
	ds_read_b128 v[192:195], v151 offset:51200
	ds_read_b128 v[196:199], v151 offset:52224
	global_load_lds_dwordx4 v132, s[42:43] offset:128
	s_add_i32 m0, s31, 0x19f80
	s_add_u32 s42, s42, 0x100080
	s_addc_u32 s43, s43, 0
	global_load_lds_dwordx4 v128, s[98:99] offset:128
	s_add_i32 m0, s31, 0x1c000
	ds_read_b128 v[200:203], v151 offset:53248
	global_load_lds_dwordx4 v132, s[42:43]
	s_add_i32 m0, s31, 0x1e000
	ds_read_b128 v[204:207], v151 offset:54272
	global_load_lds_dwordx4 v128, s[42:43]
	s_add_i32 m0, s48, -128
	ds_read_b128 v[208:211], v151 offset:55296
	global_load_lds_dwordx4 v134, s[100:101] offset:128
	s_add_i32 m0, s49, -128
	ds_read_b128 v[212:215], v151 offset:56320
	global_load_lds_dwordx4 v130, s[100:101] offset:128
	s_waitcnt vmcnt(8) lgkmcnt(0)
	s_setprio 1
	s_barrier
	v_mfma_f32_16x16x32_bf16 v[60:63], v[152:155], v[184:187], v[60:63]
	v_mfma_f32_16x16x32_bf16 v[56:59], v[160:163], v[184:187], v[56:59]
	v_mfma_f32_16x16x32_bf16 v[52:55], v[152:155], v[192:195], v[52:55]
	v_mfma_f32_16x16x32_bf16 v[44:47], v[160:163], v[192:195], v[44:47]
	v_mfma_f32_16x16x32_bf16 v[36:39], v[152:155], v[200:203], v[36:39]
	v_mfma_f32_16x16x32_bf16 v[28:31], v[160:163], v[200:203], v[28:31]
	v_mfma_f32_16x16x32_bf16 v[20:23], v[152:155], v[208:211], v[20:23]
	v_mfma_f32_16x16x32_bf16 v[12:15], v[160:163], v[208:211], v[12:15]
	v_mfma_f32_16x16x32_bf16 v[60:63], v[156:159], v[188:191], v[60:63]
	v_mfma_f32_16x16x32_bf16 v[56:59], v[164:167], v[188:191], v[56:59]
	v_mfma_f32_16x16x32_bf16 v[52:55], v[156:159], v[196:199], v[52:55]
	v_mfma_f32_16x16x32_bf16 v[44:47], v[164:167], v[196:199], v[44:47]
	v_mfma_f32_16x16x32_bf16 v[36:39], v[156:159], v[204:207], v[36:39]
	v_mfma_f32_16x16x32_bf16 v[28:31], v[164:167], v[204:207], v[28:31]
	v_mfma_f32_16x16x32_bf16 v[20:23], v[156:159], v[212:215], v[20:23]
	v_mfma_f32_16x16x32_bf16 v[12:15], v[164:167], v[212:215], v[12:15]
	v_mfma_f32_16x16x32_bf16 v[48:51], v[168:171], v[184:187], v[48:51]
	v_mfma_f32_16x16x32_bf16 v[40:43], v[176:179], v[184:187], v[40:43]
	v_mfma_f32_16x16x32_bf16 v[32:35], v[168:171], v[192:195], v[32:35]
	v_mfma_f32_16x16x32_bf16 v[24:27], v[176:179], v[192:195], v[24:27]
	v_mfma_f32_16x16x32_bf16 v[16:19], v[168:171], v[200:203], v[16:19]
	v_mfma_f32_16x16x32_bf16 v[8:11], v[176:179], v[200:203], v[8:11]
	v_mfma_f32_16x16x32_bf16 v[4:7], v[168:171], v[208:211], v[4:7]
	v_mfma_f32_16x16x32_bf16 v[0:3], v[176:179], v[208:211], v[0:3]
	v_mfma_f32_16x16x32_bf16 v[48:51], v[172:175], v[188:191], v[48:51]
	v_mfma_f32_16x16x32_bf16 v[40:43], v[180:183], v[188:191], v[40:43]
	v_mfma_f32_16x16x32_bf16 v[32:35], v[172:175], v[196:199], v[32:35]
	v_mfma_f32_16x16x32_bf16 v[24:27], v[180:183], v[196:199], v[24:27]
	v_mfma_f32_16x16x32_bf16 v[16:19], v[172:175], v[204:207], v[16:19]
	v_mfma_f32_16x16x32_bf16 v[8:11], v[180:183], v[204:207], v[8:11]
	v_mfma_f32_16x16x32_bf16 v[4:7], v[172:175], v[212:215], v[4:7]
	v_mfma_f32_16x16x32_bf16 v[0:3], v[180:183], v[212:215], v[0:3]
	s_barrier
	s_setprio 0
	s_add_i32 s61, s61, 2
	s_add_u32 s40, s40, 0x100
	s_addc_u32 s41, s41, 0
	s_add_u32 s59, s59, 0x100
	s_addc_u32 s60, s60, 0
	s_cmp_gt_u32 s61, 61
	s_cbranch_scc0 .LBB0_622
	s_and_b64 vcc, exec, s[10:11]
	s_cbranch_vccz .LBB0_625
	s_barrier

.LBB0_773:
	ds_read_b128 v[144:147], v155
	ds_read_b128 v[148:151], v155 offset:1024
	ds_read_b128 v[158:161], v155 offset:2048
	ds_read_b128 v[162:165], v155 offset:3072
	ds_read_b128 v[166:169], v156
	ds_read_b128 v[170:173], v156 offset:1024
	ds_read_b128 v[174:177], v156 offset:2048
	ds_read_b128 v[178:181], v156 offset:3072
	s_add_u32 s36, s30, 0xfff80080
	s_addc_u32 s37, s31, -1
	s_cmp_eq_u32 s52, 28
	s_cselect_b32 s39, s23, s37
	s_cselect_b32 s38, s48, s36
	s_cselect_b32 s37, s21, s51
	s_cselect_b32 s36, s49, s50
	s_add_i32 m0, s17, 0xc000
	ds_read_b128 v[182:185], v157
	ds_read_b128 v[186:189], v157 offset:1024
	ds_read_b128 v[190:193], v157 offset:2048
	ds_read_b128 v[194:197], v157 offset:3072
	ds_read_b128 v[198:201], v157 offset:4096
	ds_read_b128 v[202:205], v157 offset:5120
	ds_read_b128 v[206:209], v157 offset:6144
	global_load_lds_dwordx4 v136, s[30:31]
	s_add_i32 m0, s17, 0xe000
	ds_read_b128 v[210:213], v157 offset:7168
	global_load_lds_dwordx4 v138, s[30:31]
	s_waitcnt vmcnt(8) lgkmcnt(0)
	s_setprio 1
	s_barrier
	v_mfma_i32_16x16x64_i8 v[124:127], v[144:147], v[182:185], v[124:127]
	v_mfma_i32_16x16x64_i8 v[116:119], v[158:161], v[182:185], v[116:119]
	v_mfma_i32_16x16x64_i8 v[108:111], v[144:147], v[190:193], v[108:111]
	v_mfma_i32_16x16x64_i8 v[100:103], v[158:161], v[190:193], v[100:103]
	v_mfma_i32_16x16x64_i8 v[92:95], v[144:147], v[198:201], v[92:95]
	v_mfma_i32_16x16x64_i8 v[84:87], v[158:161], v[198:201], v[84:87]
	v_mfma_i32_16x16x64_i8 v[76:79], v[144:147], v[206:209], v[76:79]
	v_mfma_i32_16x16x64_i8 v[68:71], v[158:161], v[206:209], v[68:71]
	v_mfma_i32_16x16x64_i8 v[124:127], v[148:151], v[186:189], v[124:127]
	v_mfma_i32_16x16x64_i8 v[116:119], v[162:165], v[186:189], v[116:119]
	v_mfma_i32_16x16x64_i8 v[108:111], v[148:151], v[194:197], v[108:111]
	v_mfma_i32_16x16x64_i8 v[100:103], v[162:165], v[194:197], v[100:103]
	v_mfma_i32_16x16x64_i8 v[92:95], v[148:151], v[202:205], v[92:95]
	v_mfma_i32_16x16x64_i8 v[84:87], v[162:165], v[202:205], v[84:87]
	v_mfma_i32_16x16x64_i8 v[76:79], v[148:151], v[210:213], v[76:79]
	v_mfma_i32_16x16x64_i8 v[68:71], v[162:165], v[210:213], v[68:71]
	v_mfma_i32_16x16x64_i8 v[120:123], v[166:169], v[182:185], v[120:123]
	v_mfma_i32_16x16x64_i8 v[112:115], v[174:177], v[182:185], v[112:115]
	v_mfma_i32_16x16x64_i8 v[104:107], v[166:169], v[190:193], v[104:107]
	v_mfma_i32_16x16x64_i8 v[96:99], v[174:177], v[190:193], v[96:99]
	v_mfma_i32_16x16x64_i8 v[88:91], v[166:169], v[198:201], v[88:91]
	v_mfma_i32_16x16x64_i8 v[80:83], v[174:177], v[198:201], v[80:83]
	v_mfma_i32_16x16x64_i8 v[72:75], v[166:169], v[206:209], v[72:75]
	v_mfma_i32_16x16x64_i8 v[64:67], v[174:177], v[206:209], v[64:67]
	v_mfma_i32_16x16x64_i8 v[120:123], v[170:173], v[186:189], v[120:123]
	v_mfma_i32_16x16x64_i8 v[112:115], v[178:181], v[186:189], v[112:115]
	v_mfma_i32_16x16x64_i8 v[104:107], v[170:173], v[194:197], v[104:107]
	v_mfma_i32_16x16x64_i8 v[96:99], v[178:181], v[194:197], v[96:99]
	v_mfma_i32_16x16x64_i8 v[88:91], v[170:173], v[202:205], v[88:91]
	v_mfma_i32_16x16x64_i8 v[80:83], v[178:181], v[202:205], v[80:83]
	v_mfma_i32_16x16x64_i8 v[72:75], v[170:173], v[210:213], v[72:75]
	v_mfma_i32_16x16x64_i8 v[64:67], v[178:181], v[210:213], v[64:67]
	s_barrier
	s_setprio 0
	s_add_i32 m0, s17, 0x10000
	ds_read_b128 v[182:185], v157 offset:16384
	ds_read_b128 v[186:189], v157 offset:17408
	ds_read_b128 v[190:193], v157 offset:18432
	ds_read_b128 v[194:197], v157 offset:19456
	ds_read_b128 v[198:201], v157 offset:20480
	global_load_lds_dwordx4 v132, s[36:37]
	s_add_i32 m0, s17, 0x12000
	s_add_u32 s54, s36, 0x80000
	s_mov_b64 s[98:99], s[36:37]
	s_addc_u32 s55, s37, 0
	global_load_lds_dwordx4 v128, s[98:99]
	s_add_i32 m0, s17, 0x14000
	s_mov_b64 s[100:101], s[38:39]
	global_load_lds_dwordx4 v132, s[54:55]
	s_add_i32 m0, s17, 0x16000
	ds_read_b128 v[202:205], v157 offset:21504
	global_load_lds_dwordx4 v128, s[54:55]
	s_mov_b64 s[100:101], s[38:39]
	s_mov_b32 m0, s17
	ds_read_b128 v[206:209], v157 offset:22528
	global_load_lds_dwordx4 v134, s[100:101]
	s_mov_b32 m0, s29
	ds_read_b128 v[210:213], v157 offset:23552
	global_load_lds_dwordx4 v130, s[100:101]
	s_waitcnt vmcnt(8) lgkmcnt(0)
	s_setprio 1
	s_barrier
	v_mfma_i32_16x16x64_i8 v[60:63], v[144:147], v[182:185], v[60:63]
	v_mfma_i32_16x16x64_i8 v[52:55], v[158:161], v[182:185], v[52:55]
	v_mfma_i32_16x16x64_i8 v[44:47], v[144:147], v[190:193], v[44:47]
	v_mfma_i32_16x16x64_i8 v[36:39], v[158:161], v[190:193], v[36:39]
	v_mfma_i32_16x16x64_i8 v[28:31], v[144:147], v[198:201], v[28:31]
	v_mfma_i32_16x16x64_i8 v[20:23], v[158:161], v[198:201], v[20:23]
	v_mfma_i32_16x16x64_i8 v[12:15], v[144:147], v[206:209], v[12:15]
	v_mfma_i32_16x16x64_i8 v[4:7], v[158:161], v[206:209], v[4:7]
	v_mfma_i32_16x16x64_i8 v[60:63], v[148:151], v[186:189], v[60:63]
	v_mfma_i32_16x16x64_i8 v[52:55], v[162:165], v[186:189], v[52:55]
	v_mfma_i32_16x16x64_i8 v[44:47], v[148:151], v[194:197], v[44:47]
	v_mfma_i32_16x16x64_i8 v[36:39], v[162:165], v[194:197], v[36:39]
	v_mfma_i32_16x16x64_i8 v[28:31], v[148:151], v[202:205], v[28:31]
	v_mfma_i32_16x16x64_i8 v[20:23], v[162:165], v[202:205], v[20:23]
	v_mfma_i32_16x16x64_i8 v[12:15], v[148:151], v[210:213], v[12:15]
	v_mfma_i32_16x16x64_i8 v[4:7], v[162:165], v[210:213], v[4:7]
	v_mfma_i32_16x16x64_i8 v[56:59], v[166:169], v[182:185], v[56:59]
	v_mfma_i32_16x16x64_i8 v[48:51], v[174:177], v[182:185], v[48:51]
	v_mfma_i32_16x16x64_i8 v[40:43], v[166:169], v[190:193], v[40:43]
	v_mfma_i32_16x16x64_i8 v[32:35], v[174:177], v[190:193], v[32:35]
	v_mfma_i32_16x16x64_i8 v[24:27], v[166:169], v[198:201], v[24:27]
	v_mfma_i32_16x16x64_i8 v[16:19], v[174:177], v[198:201], v[16:19]
	v_mfma_i32_16x16x64_i8 v[8:11], v[166:169], v[206:209], v[8:11]
	v_mfma_i32_16x16x64_i8 v[0:3], v[174:177], v[206:209], v[0:3]
	v_mfma_i32_16x16x64_i8 v[56:59], v[170:173], v[186:189], v[56:59]
	v_mfma_i32_16x16x64_i8 v[48:51], v[178:181], v[186:189], v[48:51]
	v_mfma_i32_16x16x64_i8 v[40:43], v[170:173], v[194:197], v[40:43]
	v_mfma_i32_16x16x64_i8 v[32:35], v[178:181], v[194:197], v[32:35]
	v_mfma_i32_16x16x64_i8 v[24:27], v[170:173], v[202:205], v[24:27]
	v_mfma_i32_16x16x64_i8 v[16:19], v[178:181], v[202:205], v[16:19]
	v_mfma_i32_16x16x64_i8 v[8:11], v[170:173], v[210:213], v[8:11]
	v_mfma_i32_16x16x64_i8 v[0:3], v[178:181], v[210:213], v[0:3]
	s_barrier
	s_setprio 0
	ds_read_b128 v[144:147], v155 offset:32768
	ds_read_b128 v[148:151], v155 offset:33792
	ds_read_b128 v[158:161], v155 offset:34816
	ds_read_b128 v[162:165], v155 offset:35840
	ds_read_b128 v[166:169], v156 offset:32768
	ds_read_b128 v[170:173], v156 offset:33792
	ds_read_b128 v[174:177], v156 offset:34816
	ds_read_b128 v[178:181], v156 offset:35840
	s_add_u32 s38, s38, 0x80000
	s_addc_u32 s39, s39, 0
	s_mov_b32 m0, s33
	ds_read_b128 v[182:185], v157 offset:32768
	ds_read_b128 v[186:189], v157 offset:33792
	ds_read_b128 v[190:193], v157 offset:34816
	ds_read_b128 v[194:197], v157 offset:35840
	ds_read_b128 v[198:201], v157 offset:36864
	ds_read_b128 v[202:205], v157 offset:37888
	ds_read_b128 v[206:209], v157 offset:38912
	global_load_lds_dwordx4 v134, s[38:39]
	s_mov_b32 m0, s35
	ds_read_b128 v[210:213], v157 offset:39936
	global_load_lds_dwordx4 v130, s[38:39]
	s_waitcnt vmcnt(8) lgkmcnt(0)
	s_setprio 1
	s_barrier
	v_mfma_i32_16x16x64_i8 v[124:127], v[144:147], v[182:185], v[124:127]
	v_mfma_i32_16x16x64_i8 v[116:119], v[158:161], v[182:185], v[116:119]
	v_mfma_i32_16x16x64_i8 v[108:111], v[144:147], v[190:193], v[108:111]
	v_mfma_i32_16x16x64_i8 v[100:103], v[158:161], v[190:193], v[100:103]
	v_mfma_i32_16x16x64_i8 v[92:95], v[144:147], v[198:201], v[92:95]
	v_mfma_i32_16x16x64_i8 v[84:87], v[158:161], v[198:201], v[84:87]
	v_mfma_i32_16x16x64_i8 v[76:79], v[144:147], v[206:209], v[76:79]
	v_mfma_i32_16x16x64_i8 v[68:71], v[158:161], v[206:209], v[68:71]
	v_mfma_i32_16x16x64_i8 v[124:127], v[148:151], v[186:189], v[124:127]
	v_mfma_i32_16x16x64_i8 v[116:119], v[162:165], v[186:189], v[116:119]
	v_mfma_i32_16x16x64_i8 v[108:111], v[148:151], v[194:197], v[108:111]
	v_mfma_i32_16x16x64_i8 v[100:103], v[162:165], v[194:197], v[100:103]
	v_mfma_i32_16x16x64_i8 v[92:95], v[148:151], v[202:205], v[92:95]
	v_mfma_i32_16x16x64_i8 v[84:87], v[162:165], v[202:205], v[84:87]
	v_mfma_i32_16x16x64_i8 v[76:79], v[148:151], v[210:213], v[76:79]
	v_mfma_i32_16x16x64_i8 v[68:71], v[162:165], v[210:213], v[68:71]
	v_mfma_i32_16x16x64_i8 v[120:123], v[166:169], v[182:185], v[120:123]
	v_mfma_i32_16x16x64_i8 v[112:115], v[174:177], v[182:185], v[112:115]
	v_mfma_i32_16x16x64_i8 v[104:107], v[166:169], v[190:193], v[104:107]
	v_mfma_i32_16x16x64_i8 v[96:99], v[174:177], v[190:193], v[96:99]
	v_mfma_i32_16x16x64_i8 v[88:91], v[166:169], v[198:201], v[88:91]
	v_mfma_i32_16x16x64_i8 v[80:83], v[174:177], v[198:201], v[80:83]
	v_mfma_i32_16x16x64_i8 v[72:75], v[166:169], v[206:209], v[72:75]
	v_mfma_i32_16x16x64_i8 v[64:67], v[174:177], v[206:209], v[64:67]
	v_mfma_i32_16x16x64_i8 v[120:123], v[170:173], v[186:189], v[120:123]
	v_mfma_i32_16x16x64_i8 v[112:115], v[178:181], v[186:189], v[112:115]
	v_mfma_i32_16x16x64_i8 v[104:107], v[170:173], v[194:197], v[104:107]
	v_mfma_i32_16x16x64_i8 v[96:99], v[178:181], v[194:197], v[96:99]
	v_mfma_i32_16x16x64_i8 v[88:91], v[170:173], v[202:205], v[88:91]
	v_mfma_i32_16x16x64_i8 v[80:83], v[178:181], v[202:205], v[80:83]
	v_mfma_i32_16x16x64_i8 v[72:75], v[170:173], v[210:213], v[72:75]
	v_mfma_i32_16x16x64_i8 v[64:67], v[178:181], v[210:213], v[64:67]
	s_barrier
	s_setprio 0
	s_add_i32 m0, s17, 0x17f80
	ds_read_b128 v[182:185], v157 offset:49152
	ds_read_b128 v[186:189], v157 offset:50176
	ds_read_b128 v[190:193], v157 offset:51200
	ds_read_b128 v[194:197], v157 offset:52224
	global_load_lds_dwordx4 v132, s[36:37] offset:128
	s_add_i32 m0, s17, 0x19f80
	s_add_u32 s36, s36, 0x80080
	s_addc_u32 s37, s37, 0
	global_load_lds_dwordx4 v128, s[98:99] offset:128
	s_add_i32 m0, s17, 0x1c000
	ds_read_b128 v[198:201], v157 offset:53248
	global_load_lds_dwordx4 v132, s[36:37]
	s_add_i32 m0, s17, 0x1e000
	ds_read_b128 v[202:205], v157 offset:54272
	global_load_lds_dwordx4 v128, s[36:37]
	s_add_i32 m0, s42, -128
	ds_read_b128 v[206:209], v157 offset:55296
	global_load_lds_dwordx4 v134, s[100:101] offset:128
	s_add_i32 m0, s43, -128
	ds_read_b128 v[210:213], v157 offset:56320
	global_load_lds_dwordx4 v130, s[100:101] offset:128
	s_waitcnt vmcnt(8) lgkmcnt(0)
	s_setprio 1
	s_barrier
	v_mfma_i32_16x16x64_i8 v[60:63], v[144:147], v[182:185], v[60:63]
	v_mfma_i32_16x16x64_i8 v[52:55], v[158:161], v[182:185], v[52:55]
	v_mfma_i32_16x16x64_i8 v[44:47], v[144:147], v[190:193], v[44:47]
	v_mfma_i32_16x16x64_i8 v[36:39], v[158:161], v[190:193], v[36:39]
	v_mfma_i32_16x16x64_i8 v[28:31], v[144:147], v[198:201], v[28:31]
	v_mfma_i32_16x16x64_i8 v[20:23], v[158:161], v[198:201], v[20:23]
	v_mfma_i32_16x16x64_i8 v[12:15], v[144:147], v[206:209], v[12:15]
	v_mfma_i32_16x16x64_i8 v[4:7], v[158:161], v[206:209], v[4:7]
	v_mfma_i32_16x16x64_i8 v[60:63], v[148:151], v[186:189], v[60:63]
	v_mfma_i32_16x16x64_i8 v[52:55], v[162:165], v[186:189], v[52:55]
	v_mfma_i32_16x16x64_i8 v[44:47], v[148:151], v[194:197], v[44:47]
	v_mfma_i32_16x16x64_i8 v[36:39], v[162:165], v[194:197], v[36:39]
	v_mfma_i32_16x16x64_i8 v[28:31], v[148:151], v[202:205], v[28:31]
	v_mfma_i32_16x16x64_i8 v[20:23], v[162:165], v[202:205], v[20:23]
	v_mfma_i32_16x16x64_i8 v[12:15], v[148:151], v[210:213], v[12:15]
	v_mfma_i32_16x16x64_i8 v[4:7], v[162:165], v[210:213], v[4:7]
	v_mfma_i32_16x16x64_i8 v[56:59], v[166:169], v[182:185], v[56:59]
	v_mfma_i32_16x16x64_i8 v[48:51], v[174:177], v[182:185], v[48:51]
	v_mfma_i32_16x16x64_i8 v[40:43], v[166:169], v[190:193], v[40:43]
	v_mfma_i32_16x16x64_i8 v[32:35], v[174:177], v[190:193], v[32:35]
	v_mfma_i32_16x16x64_i8 v[24:27], v[166:169], v[198:201], v[24:27]
	v_mfma_i32_16x16x64_i8 v[16:19], v[174:177], v[198:201], v[16:19]
	v_mfma_i32_16x16x64_i8 v[8:11], v[166:169], v[206:209], v[8:11]
	v_mfma_i32_16x16x64_i8 v[0:3], v[174:177], v[206:209], v[0:3]
	v_mfma_i32_16x16x64_i8 v[56:59], v[170:173], v[186:189], v[56:59]
	v_mfma_i32_16x16x64_i8 v[48:51], v[178:181], v[186:189], v[48:51]
	v_mfma_i32_16x16x64_i8 v[40:43], v[170:173], v[194:197], v[40:43]
	v_mfma_i32_16x16x64_i8 v[32:35], v[178:181], v[194:197], v[32:35]
	v_mfma_i32_16x16x64_i8 v[24:27], v[170:173], v[202:205], v[24:27]
	v_mfma_i32_16x16x64_i8 v[16:19], v[178:181], v[202:205], v[16:19]
	v_mfma_i32_16x16x64_i8 v[8:11], v[170:173], v[210:213], v[8:11]
	v_mfma_i32_16x16x64_i8 v[0:3], v[178:181], v[210:213], v[0:3]
	s_barrier
	s_setprio 0
	s_add_i32 s52, s52, 2
	s_add_u32 s30, s30, 0x100
	s_addc_u32 s31, s31, 0
	s_add_u32 s50, s50, 0x100
	s_addc_u32 s51, s51, 0
	s_cmp_gt_u32 s52, 29
	s_cbranch_scc0 .LBB0_773
	s_and_b64 vcc, exec, s[14:15]
	s_cbranch_vccz .LBB0_776
	s_barrier

.LBB0_858:
	ds_read_b128 v[152:155], v149
	ds_read_b128 v[156:159], v149 offset:1024
	ds_read_b128 v[160:163], v149 offset:2048
	ds_read_b128 v[164:167], v149 offset:3072
	ds_read_b128 v[168:171], v150
	ds_read_b128 v[172:175], v150 offset:1024
	ds_read_b128 v[176:179], v150 offset:2048
	ds_read_b128 v[180:183], v150 offset:3072
	s_add_u32 s26, s24, 0x100
	s_addc_u32 s27, s25, 0
	s_cmpk_eq_i32 s54, 0xa8
	s_cselect_b32 s31, s5, s27
	s_cselect_b32 s30, s4, s26
	s_cselect_b32 s29, s23, s53
	s_cselect_b32 s28, s22, s52
	s_add_i32 m0, s33, 0xc000
	ds_read_b128 v[184:187], v151
	ds_read_b128 v[188:191], v151 offset:1024
	ds_read_b128 v[192:195], v151 offset:2048
	ds_read_b128 v[196:199], v151 offset:3072
	ds_read_b128 v[200:203], v151 offset:4096
	ds_read_b128 v[204:207], v151 offset:5120
	ds_read_b128 v[208:211], v151 offset:6144
	global_load_lds_dwordx4 v136, s[24:25]
	s_add_i32 m0, s33, 0xe000
	ds_read_b128 v[212:215], v151 offset:7168
	global_load_lds_dwordx4 v138, s[24:25]
	s_waitcnt vmcnt(8) lgkmcnt(0)
	s_setprio 1
	s_barrier
	v_mfma_f32_16x16x32_bf16 v[124:127], v[152:155], v[184:187], v[124:127]
	v_mfma_f32_16x16x32_bf16 v[120:123], v[160:163], v[184:187], v[120:123]
	v_mfma_f32_16x16x32_bf16 v[116:119], v[152:155], v[192:195], v[116:119]
	v_mfma_f32_16x16x32_bf16 v[108:111], v[160:163], v[192:195], v[108:111]
	v_mfma_f32_16x16x32_bf16 v[100:103], v[152:155], v[200:203], v[100:103]
	v_mfma_f32_16x16x32_bf16 v[92:95], v[160:163], v[200:203], v[92:95]
	v_mfma_f32_16x16x32_bf16 v[84:87], v[152:155], v[208:211], v[84:87]
	v_mfma_f32_16x16x32_bf16 v[76:79], v[160:163], v[208:211], v[76:79]
	v_mfma_f32_16x16x32_bf16 v[124:127], v[156:159], v[188:191], v[124:127]
	v_mfma_f32_16x16x32_bf16 v[120:123], v[164:167], v[188:191], v[120:123]
	v_mfma_f32_16x16x32_bf16 v[116:119], v[156:159], v[196:199], v[116:119]
	v_mfma_f32_16x16x32_bf16 v[108:111], v[164:167], v[196:199], v[108:111]
	v_mfma_f32_16x16x32_bf16 v[100:103], v[156:159], v[204:207], v[100:103]
	v_mfma_f32_16x16x32_bf16 v[92:95], v[164:167], v[204:207], v[92:95]
	v_mfma_f32_16x16x32_bf16 v[84:87], v[156:159], v[212:215], v[84:87]
	v_mfma_f32_16x16x32_bf16 v[76:79], v[164:167], v[212:215], v[76:79]
	v_mfma_f32_16x16x32_bf16 v[112:115], v[168:171], v[184:187], v[112:115]
	v_mfma_f32_16x16x32_bf16 v[104:107], v[176:179], v[184:187], v[104:107]
	v_mfma_f32_16x16x32_bf16 v[96:99], v[168:171], v[192:195], v[96:99]
	v_mfma_f32_16x16x32_bf16 v[88:91], v[176:179], v[192:195], v[88:91]
	v_mfma_f32_16x16x32_bf16 v[80:83], v[168:171], v[200:203], v[80:83]
	v_mfma_f32_16x16x32_bf16 v[72:75], v[176:179], v[200:203], v[72:75]
	v_mfma_f32_16x16x32_bf16 v[68:71], v[168:171], v[208:211], v[68:71]
	v_mfma_f32_16x16x32_bf16 v[64:67], v[176:179], v[208:211], v[64:67]
	v_mfma_f32_16x16x32_bf16 v[112:115], v[172:175], v[188:191], v[112:115]
	v_mfma_f32_16x16x32_bf16 v[104:107], v[180:183], v[188:191], v[104:107]
	v_mfma_f32_16x16x32_bf16 v[96:99], v[172:175], v[196:199], v[96:99]
	v_mfma_f32_16x16x32_bf16 v[88:91], v[180:183], v[196:199], v[88:91]
	v_mfma_f32_16x16x32_bf16 v[80:83], v[172:175], v[204:207], v[80:83]
	v_mfma_f32_16x16x32_bf16 v[72:75], v[180:183], v[204:207], v[72:75]
	v_mfma_f32_16x16x32_bf16 v[68:71], v[172:175], v[212:215], v[68:71]
	v_mfma_f32_16x16x32_bf16 v[64:67], v[180:183], v[212:215], v[64:67]
	s_barrier
	s_setprio 0
	s_add_i32 m0, s33, 0x10000
	ds_read_b128 v[184:187], v151 offset:16384
	ds_read_b128 v[188:191], v151 offset:17408
	ds_read_b128 v[192:195], v151 offset:18432
	ds_read_b128 v[196:199], v151 offset:19456
	global_load_lds_dwordx4 v132, s[28:29]
	s_add_i32 m0, s33, 0x12000
	s_add_u32 s24, s28, 0x2b0000
	s_mov_b64 s[98:99], s[28:29]
	s_addc_u32 s25, s29, 0
	global_load_lds_dwordx4 v128, s[98:99]
	s_add_i32 m0, s33, 0x14000
	ds_read_b128 v[200:203], v151 offset:20480
	global_load_lds_dwordx4 v132, s[24:25]
	s_add_i32 m0, s33, 0x16000
	ds_read_b128 v[204:207], v151 offset:21504
	global_load_lds_dwordx4 v128, s[24:25]
	s_mov_b32 m0, s33
	ds_read_b128 v[208:211], v151 offset:22528
	global_load_lds_dwordx4 v134, s[30:31]
	s_mov_b32 m0, s35
	ds_read_b128 v[212:215], v151 offset:23552
	global_load_lds_dwordx4 v130, s[30:31]
	s_waitcnt vmcnt(8) lgkmcnt(0)
	s_setprio 1
	s_barrier
	v_mfma_f32_16x16x32_bf16 v[60:63], v[152:155], v[184:187], v[60:63]
	v_mfma_f32_16x16x32_bf16 v[56:59], v[160:163], v[184:187], v[56:59]
	v_mfma_f32_16x16x32_bf16 v[52:55], v[152:155], v[192:195], v[52:55]
	v_mfma_f32_16x16x32_bf16 v[44:47], v[160:163], v[192:195], v[44:47]
	v_mfma_f32_16x16x32_bf16 v[36:39], v[152:155], v[200:203], v[36:39]
	v_mfma_f32_16x16x32_bf16 v[28:31], v[160:163], v[200:203], v[28:31]
	v_mfma_f32_16x16x32_bf16 v[20:23], v[152:155], v[208:211], v[20:23]
	v_mfma_f32_16x16x32_bf16 v[12:15], v[160:163], v[208:211], v[12:15]
	v_mfma_f32_16x16x32_bf16 v[60:63], v[156:159], v[188:191], v[60:63]
	v_mfma_f32_16x16x32_bf16 v[56:59], v[164:167], v[188:191], v[56:59]
	v_mfma_f32_16x16x32_bf16 v[52:55], v[156:159], v[196:199], v[52:55]
	v_mfma_f32_16x16x32_bf16 v[44:47], v[164:167], v[196:199], v[44:47]
	v_mfma_f32_16x16x32_bf16 v[36:39], v[156:159], v[204:207], v[36:39]
	v_mfma_f32_16x16x32_bf16 v[28:31], v[164:167], v[204:207], v[28:31]
	v_mfma_f32_16x16x32_bf16 v[20:23], v[156:159], v[212:215], v[20:23]
	v_mfma_f32_16x16x32_bf16 v[12:15], v[164:167], v[212:215], v[12:15]
	v_mfma_f32_16x16x32_bf16 v[48:51], v[168:171], v[184:187], v[48:51]
	v_mfma_f32_16x16x32_bf16 v[40:43], v[176:179], v[184:187], v[40:43]
	v_mfma_f32_16x16x32_bf16 v[32:35], v[168:171], v[192:195], v[32:35]
	v_mfma_f32_16x16x32_bf16 v[24:27], v[176:179], v[192:195], v[24:27]
	v_mfma_f32_16x16x32_bf16 v[16:19], v[168:171], v[200:203], v[16:19]
	v_mfma_f32_16x16x32_bf16 v[8:11], v[176:179], v[200:203], v[8:11]
	v_mfma_f32_16x16x32_bf16 v[4:7], v[168:171], v[208:211], v[4:7]
	v_mfma_f32_16x16x32_bf16 v[0:3], v[176:179], v[208:211], v[0:3]
	v_mfma_f32_16x16x32_bf16 v[48:51], v[172:175], v[188:191], v[48:51]
	v_mfma_f32_16x16x32_bf16 v[40:43], v[180:183], v[188:191], v[40:43]
	v_mfma_f32_16x16x32_bf16 v[32:35], v[172:175], v[196:199], v[32:35]
	v_mfma_f32_16x16x32_bf16 v[24:27], v[180:183], v[196:199], v[24:27]
	v_mfma_f32_16x16x32_bf16 v[16:19], v[172:175], v[204:207], v[16:19]
	v_mfma_f32_16x16x32_bf16 v[8:11], v[180:183], v[204:207], v[8:11]
	v_mfma_f32_16x16x32_bf16 v[4:7], v[172:175], v[212:215], v[4:7]
	v_mfma_f32_16x16x32_bf16 v[0:3], v[180:183], v[212:215], v[0:3]
	s_barrier
	s_setprio 0
	ds_read_b128 v[152:155], v149 offset:32768
	ds_read_b128 v[156:159], v149 offset:33792
	ds_read_b128 v[160:163], v149 offset:34816
	ds_read_b128 v[164:167], v149 offset:35840
	ds_read_b128 v[168:171], v150 offset:32768
	ds_read_b128 v[172:175], v150 offset:33792
	ds_read_b128 v[176:179], v150 offset:34816
	ds_read_b128 v[180:183], v150 offset:35840
	s_add_u32 s24, s30, 0x2b0000
	s_addc_u32 s25, s31, 0
	s_mov_b32 m0, s36
	ds_read_b128 v[184:187], v151 offset:32768
	ds_read_b128 v[188:191], v151 offset:33792
	ds_read_b128 v[192:195], v151 offset:34816
	ds_read_b128 v[196:199], v151 offset:35840
	ds_read_b128 v[200:203], v151 offset:36864
	ds_read_b128 v[204:207], v151 offset:37888
	ds_read_b128 v[208:211], v151 offset:38912
	global_load_lds_dwordx4 v134, s[24:25]
	s_mov_b32 m0, s37
	ds_read_b128 v[212:215], v151 offset:39936
	global_load_lds_dwordx4 v130, s[24:25]
	s_waitcnt vmcnt(8) lgkmcnt(0)
	s_setprio 1
	s_barrier
	v_mfma_f32_16x16x32_bf16 v[124:127], v[152:155], v[184:187], v[124:127]
	v_mfma_f32_16x16x32_bf16 v[120:123], v[160:163], v[184:187], v[120:123]
	v_mfma_f32_16x16x32_bf16 v[116:119], v[152:155], v[192:195], v[116:119]
	v_mfma_f32_16x16x32_bf16 v[108:111], v[160:163], v[192:195], v[108:111]
	v_mfma_f32_16x16x32_bf16 v[100:103], v[152:155], v[200:203], v[100:103]
	v_mfma_f32_16x16x32_bf16 v[92:95], v[160:163], v[200:203], v[92:95]
	v_mfma_f32_16x16x32_bf16 v[84:87], v[152:155], v[208:211], v[84:87]
	v_mfma_f32_16x16x32_bf16 v[76:79], v[160:163], v[208:211], v[76:79]
	v_mfma_f32_16x16x32_bf16 v[124:127], v[156:159], v[188:191], v[124:127]
	v_mfma_f32_16x16x32_bf16 v[120:123], v[164:167], v[188:191], v[120:123]
	v_mfma_f32_16x16x32_bf16 v[116:119], v[156:159], v[196:199], v[116:119]
	v_mfma_f32_16x16x32_bf16 v[108:111], v[164:167], v[196:199], v[108:111]
	v_mfma_f32_16x16x32_bf16 v[100:103], v[156:159], v[204:207], v[100:103]
	v_mfma_f32_16x16x32_bf16 v[92:95], v[164:167], v[204:207], v[92:95]
	v_mfma_f32_16x16x32_bf16 v[84:87], v[156:159], v[212:215], v[84:87]
	v_mfma_f32_16x16x32_bf16 v[76:79], v[164:167], v[212:215], v[76:79]
	v_mfma_f32_16x16x32_bf16 v[112:115], v[168:171], v[184:187], v[112:115]
	v_mfma_f32_16x16x32_bf16 v[104:107], v[176:179], v[184:187], v[104:107]
	v_mfma_f32_16x16x32_bf16 v[96:99], v[168:171], v[192:195], v[96:99]
	v_mfma_f32_16x16x32_bf16 v[88:91], v[176:179], v[192:195], v[88:91]
	v_mfma_f32_16x16x32_bf16 v[80:83], v[168:171], v[200:203], v[80:83]
	v_mfma_f32_16x16x32_bf16 v[72:75], v[176:179], v[200:203], v[72:75]
	v_mfma_f32_16x16x32_bf16 v[68:71], v[168:171], v[208:211], v[68:71]
	v_mfma_f32_16x16x32_bf16 v[64:67], v[176:179], v[208:211], v[64:67]
	v_mfma_f32_16x16x32_bf16 v[112:115], v[172:175], v[188:191], v[112:115]
	v_mfma_f32_16x16x32_bf16 v[104:107], v[180:183], v[188:191], v[104:107]
	v_mfma_f32_16x16x32_bf16 v[96:99], v[172:175], v[196:199], v[96:99]
	v_mfma_f32_16x16x32_bf16 v[88:91], v[180:183], v[196:199], v[88:91]
	v_mfma_f32_16x16x32_bf16 v[80:83], v[172:175], v[204:207], v[80:83]
	v_mfma_f32_16x16x32_bf16 v[72:75], v[180:183], v[204:207], v[72:75]
	v_mfma_f32_16x16x32_bf16 v[68:71], v[172:175], v[212:215], v[68:71]
	v_mfma_f32_16x16x32_bf16 v[64:67], v[180:183], v[212:215], v[64:67]
	s_barrier
	s_setprio 0
	s_add_i32 m0, s33, 0x17f80
	ds_read_b128 v[184:187], v151 offset:49152
	ds_read_b128 v[188:191], v151 offset:50176
	ds_read_b128 v[192:195], v151 offset:51200
	ds_read_b128 v[196:199], v151 offset:52224
	global_load_lds_dwordx4 v132, s[28:29] offset:128
	s_add_i32 m0, s33, 0x19f80
	s_add_u32 s24, s28, 0x2b0080
	s_addc_u32 s25, s29, 0
	global_load_lds_dwordx4 v128, s[98:99] offset:128
	s_add_i32 m0, s33, 0x1c000
	ds_read_b128 v[200:203], v151 offset:53248
	global_load_lds_dwordx4 v132, s[24:25]
	s_add_i32 m0, s33, 0x1e000
	ds_read_b128 v[204:207], v151 offset:54272
	global_load_lds_dwordx4 v128, s[24:25]
	s_add_i32 m0, s40, -128
	ds_read_b128 v[208:211], v151 offset:55296
	global_load_lds_dwordx4 v134, s[30:31] offset:128
	s_add_i32 m0, s41, -128
	ds_read_b128 v[212:215], v151 offset:56320
	global_load_lds_dwordx4 v130, s[30:31] offset:128
	s_waitcnt vmcnt(8) lgkmcnt(0)
	s_setprio 1
	s_barrier
	v_mfma_f32_16x16x32_bf16 v[60:63], v[152:155], v[184:187], v[60:63]
	v_mfma_f32_16x16x32_bf16 v[56:59], v[160:163], v[184:187], v[56:59]
	v_mfma_f32_16x16x32_bf16 v[52:55], v[152:155], v[192:195], v[52:55]
	v_mfma_f32_16x16x32_bf16 v[44:47], v[160:163], v[192:195], v[44:47]
	v_mfma_f32_16x16x32_bf16 v[36:39], v[152:155], v[200:203], v[36:39]
	v_mfma_f32_16x16x32_bf16 v[28:31], v[160:163], v[200:203], v[28:31]
	v_mfma_f32_16x16x32_bf16 v[20:23], v[152:155], v[208:211], v[20:23]
	v_mfma_f32_16x16x32_bf16 v[12:15], v[160:163], v[208:211], v[12:15]
	v_mfma_f32_16x16x32_bf16 v[60:63], v[156:159], v[188:191], v[60:63]
	v_mfma_f32_16x16x32_bf16 v[56:59], v[164:167], v[188:191], v[56:59]
	v_mfma_f32_16x16x32_bf16 v[52:55], v[156:159], v[196:199], v[52:55]
	v_mfma_f32_16x16x32_bf16 v[44:47], v[164:167], v[196:199], v[44:47]
	v_mfma_f32_16x16x32_bf16 v[36:39], v[156:159], v[204:207], v[36:39]
	v_mfma_f32_16x16x32_bf16 v[28:31], v[164:167], v[204:207], v[28:31]
	v_mfma_f32_16x16x32_bf16 v[20:23], v[156:159], v[212:215], v[20:23]
	v_mfma_f32_16x16x32_bf16 v[12:15], v[164:167], v[212:215], v[12:15]
	v_mfma_f32_16x16x32_bf16 v[48:51], v[168:171], v[184:187], v[48:51]
	v_mfma_f32_16x16x32_bf16 v[40:43], v[176:179], v[184:187], v[40:43]
	v_mfma_f32_16x16x32_bf16 v[32:35], v[168:171], v[192:195], v[32:35]
	v_mfma_f32_16x16x32_bf16 v[24:27], v[176:179], v[192:195], v[24:27]
	v_mfma_f32_16x16x32_bf16 v[16:19], v[168:171], v[200:203], v[16:19]
	v_mfma_f32_16x16x32_bf16 v[8:11], v[176:179], v[200:203], v[8:11]
	v_mfma_f32_16x16x32_bf16 v[4:7], v[168:171], v[208:211], v[4:7]
	v_mfma_f32_16x16x32_bf16 v[0:3], v[176:179], v[208:211], v[0:3]
	v_mfma_f32_16x16x32_bf16 v[48:51], v[172:175], v[188:191], v[48:51]
	v_mfma_f32_16x16x32_bf16 v[40:43], v[180:183], v[188:191], v[40:43]
	v_mfma_f32_16x16x32_bf16 v[32:35], v[172:175], v[196:199], v[32:35]
	v_mfma_f32_16x16x32_bf16 v[24:27], v[180:183], v[196:199], v[24:27]
	v_mfma_f32_16x16x32_bf16 v[16:19], v[172:175], v[204:207], v[16:19]
	v_mfma_f32_16x16x32_bf16 v[8:11], v[180:183], v[204:207], v[8:11]
	v_mfma_f32_16x16x32_bf16 v[4:7], v[172:175], v[212:215], v[4:7]
	v_mfma_f32_16x16x32_bf16 v[0:3], v[180:183], v[212:215], v[0:3]
	s_barrier
	s_setprio 0
	s_add_i32 s54, s54, 2
	s_add_u32 s52, s52, 0x100
	s_addc_u32 s53, s53, 0
	s_cmpk_gt_u32 s54, 0xa9
	s_mov_b64 s[24:25], s[26:27]
	s_cbranch_scc0 .LBB0_858
	s_and_b64 vcc, exec, s[10:11]
	s_cbranch_vccz .LBB0_861
	s_barrier
